# GEMM K-loops: fragment ds_reads issued in MFMA consumption order, counted lgkmcnt waits between MFMA pairs instead of lgkmcnt(0) before the MMA segment
# speedup vs baseline: 1.0034x; 1.0034x over previous
.LBB0_345:
	ds_read_b128 v[164:167], v160
	ds_read_b128 v[168:171], v160 offset:1024
	ds_read_b128 v[172:175], v160 offset:2048
	ds_read_b128 v[176:179], v160 offset:3072
	s_add_u32 s46, s44, 0xfff80080
	s_addc_u32 s47, s45, -1
	s_cmp_eq_u32 s76, 28
	s_cselect_b32 s51, s37, s47
	s_cselect_b32 s50, s72, s46
	s_cselect_b32 s47, s27, s75
	s_cselect_b32 s46, s73, s74
	v_lshl_add_u64 v[148:149], s[44:45], 0, v[138:139]
	s_add_i32 m0, s34, 0xc000
	ds_read_b128 v[180:183], v161
	ds_read_b128 v[188:191], v161 offset:2048
	ds_read_b128 v[196:199], v161 offset:4096
	ds_read_b128 v[208:211], v161 offset:6144
	ds_read_b128 v[184:187], v161 offset:1024
	ds_read_b128 v[192:195], v161 offset:3072
	ds_read_b128 v[204:207], v161 offset:5120
	ds_read_b128 v[212:215], v161 offset:7168
	global_load_lds_dwordx4 v[148:149], off
	v_lshl_add_u64 v[148:149], s[44:45], 0, v[140:141]
	s_add_i32 m0, s34, 0xe000
	s_nop 0
	global_load_lds_dwordx4 v[148:149], off
	s_waitcnt lgkmcnt(8)
	s_barrier
	s_setprio 1
	s_waitcnt lgkmcnt(7)
	v_mfma_f32_16x16x32_bf16 v[126:129], v[164:167], v[180:183], v[126:129]
	v_mfma_f32_16x16x32_bf16 v[122:125], v[172:175], v[180:183], v[122:125]
	s_waitcnt lgkmcnt(6)
	v_mfma_f32_16x16x32_bf16 v[114:117], v[164:167], v[188:191], v[114:117]
	v_mfma_f32_16x16x32_bf16 v[106:109], v[172:175], v[188:191], v[106:109]
	s_waitcnt lgkmcnt(5)
	v_mfma_f32_16x16x32_bf16 v[98:101], v[164:167], v[196:199], v[98:101]
	v_mfma_f32_16x16x32_bf16 v[90:93], v[172:175], v[196:199], v[90:93]
	s_waitcnt lgkmcnt(4)
	v_mfma_f32_16x16x32_bf16 v[82:85], v[164:167], v[208:211], v[82:85]
	v_mfma_f32_16x16x32_bf16 v[74:77], v[172:175], v[208:211], v[74:77]
	s_waitcnt lgkmcnt(3)
	v_mfma_f32_16x16x32_bf16 v[126:129], v[168:171], v[184:187], v[126:129]
	v_mfma_f32_16x16x32_bf16 v[122:125], v[176:179], v[184:187], v[122:125]
	s_waitcnt lgkmcnt(2)
	v_mfma_f32_16x16x32_bf16 v[114:117], v[168:171], v[192:195], v[114:117]
	v_mfma_f32_16x16x32_bf16 v[106:109], v[176:179], v[192:195], v[106:109]
	s_waitcnt lgkmcnt(1)
	v_mfma_f32_16x16x32_bf16 v[98:101], v[168:171], v[204:207], v[98:101]
	v_mfma_f32_16x16x32_bf16 v[90:93], v[176:179], v[204:207], v[90:93]
	s_waitcnt lgkmcnt(0)
	v_mfma_f32_16x16x32_bf16 v[82:85], v[168:171], v[212:215], v[82:85]
	v_mfma_f32_16x16x32_bf16 v[74:77], v[176:179], v[212:215], v[74:77]
	s_setprio 0
	s_barrier
	s_add_i32 s77, s65, s33
	v_lshl_add_u64 v[148:149], s[46:47], 0, v[132:133]
	s_mov_b32 m0, s77
	ds_read_b128 v[216:219], v162
	ds_read_b128 v[224:227], v162 offset:2048
	ds_read_b128 v[220:223], v162 offset:1024
	ds_read_b128 v[228:231], v162 offset:3072
	global_load_lds_dwordx4 v[148:149], off
	v_lshl_add_u64 v[232:233], s[46:47], 0, v[136:137]
	s_add_i32 m0, s77, 0x2000
	s_nop 0
	global_load_lds_dwordx4 v[232:233], off
	s_barrier
	s_setprio 1
	s_waitcnt lgkmcnt(2)
	v_mfma_f32_16x16x32_bf16 v[118:121], v[216:219], v[180:183], v[118:121]
	v_mfma_f32_16x16x32_bf16 v[110:113], v[224:227], v[180:183], v[110:113]
	v_mfma_f32_16x16x32_bf16 v[102:105], v[216:219], v[188:191], v[102:105]
	v_mfma_f32_16x16x32_bf16 v[94:97], v[224:227], v[188:191], v[94:97]
	v_mfma_f32_16x16x32_bf16 v[86:89], v[216:219], v[196:199], v[86:89]
	v_mfma_f32_16x16x32_bf16 v[78:81], v[224:227], v[196:199], v[78:81]
	v_mfma_f32_16x16x32_bf16 v[70:73], v[216:219], v[208:211], v[70:73]
	v_mfma_f32_16x16x32_bf16 v[66:69], v[224:227], v[208:211], v[66:69]
	s_waitcnt lgkmcnt(0)
	v_mfma_f32_16x16x32_bf16 v[118:121], v[220:223], v[184:187], v[118:121]
	v_mfma_f32_16x16x32_bf16 v[110:113], v[228:231], v[184:187], v[110:113]
	v_mfma_f32_16x16x32_bf16 v[102:105], v[220:223], v[192:195], v[102:105]
	v_mfma_f32_16x16x32_bf16 v[94:97], v[228:231], v[192:195], v[94:97]
	v_mfma_f32_16x16x32_bf16 v[86:89], v[220:223], v[204:207], v[86:89]
	v_mfma_f32_16x16x32_bf16 v[78:81], v[228:231], v[204:207], v[78:81]
	v_mfma_f32_16x16x32_bf16 v[70:73], v[220:223], v[212:215], v[70:73]
	v_mfma_f32_16x16x32_bf16 v[66:69], v[228:231], v[212:215], v[66:69]
	s_setprio 0
	s_mov_b32 m0, s34
	v_lshl_add_u64 v[234:235], s[50:51], 0, v[130:131]
	s_barrier
	ds_read_b128 v[180:183], v161 offset:16384
	ds_read_b128 v[188:191], v161 offset:18432
	ds_read_b128 v[196:199], v161 offset:20480
	ds_read_b128 v[208:211], v161 offset:22528
	ds_read_b128 v[184:187], v161 offset:17408
	ds_read_b128 v[192:195], v161 offset:19456
	ds_read_b128 v[204:207], v161 offset:21504
	ds_read_b128 v[212:215], v161 offset:23552
	global_load_lds_dwordx4 v[234:235], off
	v_lshl_add_u64 v[236:237], s[50:51], 0, v[134:135]
	s_mov_b32 m0, s35
	s_nop 0
	global_load_lds_dwordx4 v[236:237], off
	s_barrier
	s_setprio 1
	s_waitcnt lgkmcnt(7)
	v_mfma_f32_16x16x32_bf16 v[62:65], v[164:167], v[180:183], v[62:65]
	v_mfma_f32_16x16x32_bf16 v[58:61], v[172:175], v[180:183], v[58:61]
	s_waitcnt lgkmcnt(6)
	v_mfma_f32_16x16x32_bf16 v[54:57], v[164:167], v[188:191], v[54:57]
	v_mfma_f32_16x16x32_bf16 v[46:49], v[172:175], v[188:191], v[46:49]
	s_waitcnt lgkmcnt(5)
	v_mfma_f32_16x16x32_bf16 v[38:41], v[164:167], v[196:199], v[38:41]
	v_mfma_f32_16x16x32_bf16 v[30:33], v[172:175], v[196:199], v[30:33]
	s_waitcnt lgkmcnt(4)
	v_mfma_f32_16x16x32_bf16 v[22:25], v[164:167], v[208:211], v[22:25]
	v_mfma_f32_16x16x32_bf16 v[14:17], v[172:175], v[208:211], v[14:17]
	s_waitcnt lgkmcnt(3)
	v_mfma_f32_16x16x32_bf16 v[62:65], v[168:171], v[184:187], v[62:65]
	v_mfma_f32_16x16x32_bf16 v[58:61], v[176:179], v[184:187], v[58:61]
	s_waitcnt lgkmcnt(2)
	v_mfma_f32_16x16x32_bf16 v[54:57], v[168:171], v[192:195], v[54:57]
	v_mfma_f32_16x16x32_bf16 v[46:49], v[176:179], v[192:195], v[46:49]
	s_waitcnt lgkmcnt(1)
	v_mfma_f32_16x16x32_bf16 v[38:41], v[168:171], v[204:207], v[38:41]
	v_mfma_f32_16x16x32_bf16 v[30:33], v[176:179], v[204:207], v[30:33]
	s_waitcnt lgkmcnt(0)
	v_mfma_f32_16x16x32_bf16 v[22:25], v[168:171], v[212:215], v[22:25]
	v_mfma_f32_16x16x32_bf16 v[14:17], v[176:179], v[212:215], v[14:17]
	s_setprio 0
	s_barrier
	s_add_u32 s78, s46, 0x80000
	s_addc_u32 s79, s47, 0
	s_add_i32 s77, s66, s33
	v_lshl_add_u64 v[164:165], s[78:79], 0, v[132:133]
	s_mov_b32 m0, s77
	s_nop 0
	global_load_lds_dwordx4 v[164:165], off
	v_lshl_add_u64 v[164:165], s[78:79], 0, v[136:137]
	s_add_i32 m0, s77, 0x2000
	s_nop 0
	global_load_lds_dwordx4 v[164:165], off
	s_waitcnt vmcnt(6)
	s_barrier
	s_setprio 1
	v_mfma_f32_16x16x32_bf16 v[50:53], v[216:219], v[180:183], v[50:53]
	v_mfma_f32_16x16x32_bf16 v[42:45], v[224:227], v[180:183], v[42:45]
	v_mfma_f32_16x16x32_bf16 v[34:37], v[216:219], v[188:191], v[34:37]
	v_mfma_f32_16x16x32_bf16 v[26:29], v[224:227], v[188:191], v[26:29]
	v_mfma_f32_16x16x32_bf16 v[18:21], v[216:219], v[196:199], v[18:21]
	v_mfma_f32_16x16x32_bf16 v[10:13], v[224:227], v[196:199], v[10:13]
	v_mfma_f32_16x16x32_bf16 v[6:9], v[216:219], v[208:211], v[6:9]
	v_mfma_f32_16x16x32_bf16 v[2:5], v[224:227], v[208:211], v[2:5]
	v_mfma_f32_16x16x32_bf16 v[50:53], v[220:223], v[184:187], v[50:53]
	v_mfma_f32_16x16x32_bf16 v[42:45], v[228:231], v[184:187], v[42:45]
	v_mfma_f32_16x16x32_bf16 v[34:37], v[220:223], v[192:195], v[34:37]
	v_mfma_f32_16x16x32_bf16 v[26:29], v[228:231], v[192:195], v[26:29]
	v_mfma_f32_16x16x32_bf16 v[18:21], v[220:223], v[204:207], v[18:21]
	v_mfma_f32_16x16x32_bf16 v[10:13], v[228:231], v[204:207], v[10:13]
	v_mfma_f32_16x16x32_bf16 v[6:9], v[220:223], v[212:215], v[6:9]
	v_mfma_f32_16x16x32_bf16 v[2:5], v[228:231], v[212:215], v[2:5]
	s_setprio 0
	s_add_i32 s77, 0, 0x18000
	v_add_u32_e32 v163, s77, v158
	s_barrier
.Ltb_mid_g1:
	ds_read_b128 v[164:167], v163
	ds_read_b128 v[168:171], v163 offset:1024
	ds_read_b128 v[172:175], v163 offset:2048
	ds_read_b128 v[176:179], v163 offset:3072
	s_add_u32 s50, s50, 0x80000
	s_addc_u32 s51, s51, 0
	s_mov_b32 m0, s43
	v_lshl_add_u64 v[216:217], s[50:51], 0, v[130:131]
	ds_read_b128 v[180:183], v161 offset:32768
	ds_read_b128 v[188:191], v161 offset:34816
	ds_read_b128 v[196:199], v161 offset:36864
	ds_read_b128 v[208:211], v161 offset:38912
	ds_read_b128 v[184:187], v161 offset:33792
	ds_read_b128 v[192:195], v161 offset:35840
	ds_read_b128 v[204:207], v161 offset:37888
	ds_read_b128 v[212:215], v161 offset:39936
	global_load_lds_dwordx4 v[216:217], off
	v_lshl_add_u64 v[216:217], s[50:51], 0, v[134:135]
	s_mov_b32 m0, s60
	s_nop 0
	global_load_lds_dwordx4 v[216:217], off
	s_waitcnt lgkmcnt(8)
	s_barrier
	s_setprio 1
	s_waitcnt lgkmcnt(7)
	v_mfma_f32_16x16x32_bf16 v[126:129], v[164:167], v[180:183], v[126:129]
	v_mfma_f32_16x16x32_bf16 v[122:125], v[172:175], v[180:183], v[122:125]
	s_waitcnt lgkmcnt(6)
	v_mfma_f32_16x16x32_bf16 v[114:117], v[164:167], v[188:191], v[114:117]
	v_mfma_f32_16x16x32_bf16 v[106:109], v[172:175], v[188:191], v[106:109]
	s_waitcnt lgkmcnt(5)
	v_mfma_f32_16x16x32_bf16 v[98:101], v[164:167], v[196:199], v[98:101]
	v_mfma_f32_16x16x32_bf16 v[90:93], v[172:175], v[196:199], v[90:93]
	s_waitcnt lgkmcnt(4)
	v_mfma_f32_16x16x32_bf16 v[82:85], v[164:167], v[208:211], v[82:85]
	v_mfma_f32_16x16x32_bf16 v[74:77], v[172:175], v[208:211], v[74:77]
	s_waitcnt lgkmcnt(3)
	v_mfma_f32_16x16x32_bf16 v[126:129], v[168:171], v[184:187], v[126:129]
	v_mfma_f32_16x16x32_bf16 v[122:125], v[176:179], v[184:187], v[122:125]
	s_waitcnt lgkmcnt(2)
	v_mfma_f32_16x16x32_bf16 v[114:117], v[168:171], v[192:195], v[114:117]
	v_mfma_f32_16x16x32_bf16 v[106:109], v[176:179], v[192:195], v[106:109]
	s_waitcnt lgkmcnt(1)
	v_mfma_f32_16x16x32_bf16 v[98:101], v[168:171], v[204:207], v[98:101]
	v_mfma_f32_16x16x32_bf16 v[90:93], v[176:179], v[204:207], v[90:93]
	s_waitcnt lgkmcnt(0)
	v_mfma_f32_16x16x32_bf16 v[82:85], v[168:171], v[212:215], v[82:85]
	v_mfma_f32_16x16x32_bf16 v[74:77], v[176:179], v[212:215], v[74:77]
	s_setprio 0
	s_barrier
	s_add_i32 s50, 0, 0x1c000
	s_add_i32 s51, s77, s33
	v_add_u32_e32 v163, s50, v158
	v_lshl_add_u64 v[148:149], v[148:149], 0, s[8:9]
	s_mov_b32 m0, s51
	ds_read_b128 v[216:219], v163
	ds_read_b128 v[224:227], v163 offset:2048
	ds_read_b128 v[220:223], v163 offset:1024
	ds_read_b128 v[228:231], v163 offset:3072
	global_load_lds_dwordx4 v[148:149], off
	v_lshl_add_u64 v[148:149], v[232:233], 0, s[8:9]
	s_add_i32 m0, s51, 0x2000
	s_nop 0
	global_load_lds_dwordx4 v[148:149], off
	s_barrier
	s_setprio 1
	s_waitcnt lgkmcnt(2)
	v_mfma_f32_16x16x32_bf16 v[118:121], v[216:219], v[180:183], v[118:121]
	v_mfma_f32_16x16x32_bf16 v[110:113], v[224:227], v[180:183], v[110:113]
	v_mfma_f32_16x16x32_bf16 v[102:105], v[216:219], v[188:191], v[102:105]
	v_mfma_f32_16x16x32_bf16 v[94:97], v[224:227], v[188:191], v[94:97]
	v_mfma_f32_16x16x32_bf16 v[86:89], v[216:219], v[196:199], v[86:89]
	v_mfma_f32_16x16x32_bf16 v[78:81], v[224:227], v[196:199], v[78:81]
	v_mfma_f32_16x16x32_bf16 v[70:73], v[216:219], v[208:211], v[70:73]
	v_mfma_f32_16x16x32_bf16 v[66:69], v[224:227], v[208:211], v[66:69]
	s_waitcnt lgkmcnt(0)
	v_mfma_f32_16x16x32_bf16 v[118:121], v[220:223], v[184:187], v[118:121]
	v_mfma_f32_16x16x32_bf16 v[110:113], v[228:231], v[184:187], v[110:113]
	v_mfma_f32_16x16x32_bf16 v[102:105], v[220:223], v[192:195], v[102:105]
	v_mfma_f32_16x16x32_bf16 v[94:97], v[228:231], v[192:195], v[94:97]
	v_mfma_f32_16x16x32_bf16 v[86:89], v[220:223], v[204:207], v[86:89]
	v_mfma_f32_16x16x32_bf16 v[78:81], v[228:231], v[204:207], v[78:81]
	v_mfma_f32_16x16x32_bf16 v[70:73], v[220:223], v[212:215], v[70:73]
	v_mfma_f32_16x16x32_bf16 v[66:69], v[228:231], v[212:215], v[66:69]
	s_setprio 0
	s_mov_b32 m0, s62
	v_lshl_add_u64 v[148:149], v[234:235], 0, s[8:9]
	s_barrier
	ds_read_b128 v[180:183], v161 offset:49152
	ds_read_b128 v[188:191], v161 offset:51200
	ds_read_b128 v[196:199], v161 offset:53248
	ds_read_b128 v[208:211], v161 offset:55296
	ds_read_b128 v[184:187], v161 offset:50176
	ds_read_b128 v[192:195], v161 offset:52224
	ds_read_b128 v[204:207], v161 offset:54272
	ds_read_b128 v[212:215], v161 offset:56320
	global_load_lds_dwordx4 v[148:149], off
	v_lshl_add_u64 v[148:149], v[236:237], 0, s[8:9]
	s_mov_b32 m0, s63
	s_nop 0
	global_load_lds_dwordx4 v[148:149], off
	s_barrier
	s_setprio 1
	s_waitcnt lgkmcnt(7)
	v_mfma_f32_16x16x32_bf16 v[62:65], v[164:167], v[180:183], v[62:65]
	v_mfma_f32_16x16x32_bf16 v[58:61], v[172:175], v[180:183], v[58:61]
	s_waitcnt lgkmcnt(6)
	v_mfma_f32_16x16x32_bf16 v[54:57], v[164:167], v[188:191], v[54:57]
	v_mfma_f32_16x16x32_bf16 v[46:49], v[172:175], v[188:191], v[46:49]
	s_waitcnt lgkmcnt(5)
	v_mfma_f32_16x16x32_bf16 v[38:41], v[164:167], v[196:199], v[38:41]
	v_mfma_f32_16x16x32_bf16 v[30:33], v[172:175], v[196:199], v[30:33]
	s_waitcnt lgkmcnt(4)
	v_mfma_f32_16x16x32_bf16 v[22:25], v[164:167], v[208:211], v[22:25]
	v_mfma_f32_16x16x32_bf16 v[14:17], v[172:175], v[208:211], v[14:17]
	s_waitcnt lgkmcnt(3)
	v_mfma_f32_16x16x32_bf16 v[62:65], v[168:171], v[184:187], v[62:65]
	v_mfma_f32_16x16x32_bf16 v[58:61], v[176:179], v[184:187], v[58:61]
	s_waitcnt lgkmcnt(2)
	v_mfma_f32_16x16x32_bf16 v[54:57], v[168:171], v[192:195], v[54:57]
	v_mfma_f32_16x16x32_bf16 v[46:49], v[176:179], v[192:195], v[46:49]
	s_waitcnt lgkmcnt(1)
	v_mfma_f32_16x16x32_bf16 v[38:41], v[168:171], v[204:207], v[38:41]
	v_mfma_f32_16x16x32_bf16 v[30:33], v[176:179], v[204:207], v[30:33]
	s_waitcnt lgkmcnt(0)
	v_mfma_f32_16x16x32_bf16 v[22:25], v[168:171], v[212:215], v[22:25]
	v_mfma_f32_16x16x32_bf16 v[14:17], v[176:179], v[212:215], v[14:17]
	s_setprio 0
	s_barrier
	s_add_u32 s46, s46, 0x80080
	s_addc_u32 s47, s47, 0
	s_add_i32 s50, s50, s33
	v_lshl_add_u64 v[148:149], s[46:47], 0, v[132:133]
	s_mov_b32 m0, s50
	s_nop 0
	global_load_lds_dwordx4 v[148:149], off
	v_lshl_add_u64 v[148:149], s[46:47], 0, v[136:137]
	s_add_i32 m0, s50, 0x2000
	s_nop 0
	global_load_lds_dwordx4 v[148:149], off
	s_waitcnt vmcnt(6)
	s_barrier
	s_setprio 1
	v_mfma_f32_16x16x32_bf16 v[50:53], v[216:219], v[180:183], v[50:53]
	v_mfma_f32_16x16x32_bf16 v[42:45], v[224:227], v[180:183], v[42:45]
	v_mfma_f32_16x16x32_bf16 v[34:37], v[216:219], v[188:191], v[34:37]
	v_mfma_f32_16x16x32_bf16 v[26:29], v[224:227], v[188:191], v[26:29]
	v_mfma_f32_16x16x32_bf16 v[18:21], v[216:219], v[196:199], v[18:21]
	v_mfma_f32_16x16x32_bf16 v[10:13], v[224:227], v[196:199], v[10:13]
	v_mfma_f32_16x16x32_bf16 v[6:9], v[216:219], v[208:211], v[6:9]
	v_mfma_f32_16x16x32_bf16 v[2:5], v[224:227], v[208:211], v[2:5]
	v_mfma_f32_16x16x32_bf16 v[50:53], v[220:223], v[184:187], v[50:53]
	v_mfma_f32_16x16x32_bf16 v[42:45], v[228:231], v[184:187], v[42:45]
	v_mfma_f32_16x16x32_bf16 v[34:37], v[220:223], v[192:195], v[34:37]
	v_mfma_f32_16x16x32_bf16 v[26:29], v[228:231], v[192:195], v[26:29]
	v_mfma_f32_16x16x32_bf16 v[18:21], v[220:223], v[204:207], v[18:21]
	v_mfma_f32_16x16x32_bf16 v[10:13], v[228:231], v[204:207], v[10:13]
	v_mfma_f32_16x16x32_bf16 v[6:9], v[220:223], v[212:215], v[6:9]
	v_mfma_f32_16x16x32_bf16 v[2:5], v[228:231], v[212:215], v[2:5]
	s_setprio 0
	s_add_i32 s76, s76, 2
	s_add_u32 s44, s44, 0x100
	s_addc_u32 s45, s45, 0
	s_add_u32 s74, s74, 0x100
	s_addc_u32 s75, s75, 0
	s_cmp_gt_u32 s76, 29
	s_barrier
	s_cbranch_scc0 .LBB0_345
	s_add_u32 s100, s72, 0x80080
	s_addc_u32 s101, s37, 0
	v_lshl_add_u64 v[148:149], s[100:101], 0, v[138:139]
	s_add_i32 m0, s34, 0xc000
	s_nop 0
	global_load_lds_dwordx4 v[148:149], off
	v_lshl_add_u64 v[148:149], s[100:101], 0, v[140:141]
	s_add_i32 m0, s34, 0xe000
	s_nop 0
	global_load_lds_dwordx4 v[148:149], off
	s_mov_b32 s99, 1
	v_lshl_add_u32 v164, s42, 8, v157
	v_lshl_or_b32 v148, s71, 8, v159
	v_ashrrev_i32_e32 v165, 31, v164
	v_ashrrev_i32_e32 v149, 31, v148
	v_lshlrev_b64 v[166:167], 16, v[164:165]
	v_lshl_add_u64 v[166:167], s[6:7], 0, v[166:167]
	v_lshlrev_b64 v[168:169], 1, v[148:149]
	v_lshl_add_u64 v[148:149], v[166:167], 0, v[168:169]
	v_cvt_pk_bf16_f32 v126, v126, v127
	v_cvt_pk_bf16_f32 v127, v128, v129
	v_cvt_pk_bf16_f32 v128, v122, v123
	v_cvt_pk_bf16_f32 v129, v124, v125
	global_store_dwordx4 v[148:149], v[126:129], off
	v_cvt_pk_bf16_f32 v118, v118, v119
	v_cvt_pk_bf16_f32 v119, v120, v121
	v_cvt_pk_bf16_f32 v120, v110, v111
	v_or_b32_e32 v110, 16, v164
	v_ashrrev_i32_e32 v111, 31, v110
	v_lshlrev_b64 v[110:111], 16, v[110:111]
	v_lshl_add_u64 v[110:111], s[6:7], 0, v[110:111]
	v_cvt_pk_bf16_f32 v121, v112, v113
	global_store_dwordx4 v[148:149], v[118:121], off offset:256
	s_mov_b32 s71, s26
	s_mov_b32 s42, s36
	v_lshl_add_u64 v[118:119], v[110:111], 0, v[168:169]
	v_cvt_pk_bf16_f32 v110, v114, v115
	v_cvt_pk_bf16_f32 v111, v116, v117
	v_cvt_pk_bf16_f32 v112, v106, v107
	v_cvt_pk_bf16_f32 v113, v108, v109
	global_store_dwordx4 v[118:119], v[110:113], off
	v_cvt_pk_bf16_f32 v102, v102, v103
	v_cvt_pk_bf16_f32 v103, v104, v105
	v_cvt_pk_bf16_f32 v104, v94, v95
	v_or_b32_e32 v94, 32, v164
	v_ashrrev_i32_e32 v95, 31, v94
	v_lshlrev_b64 v[94:95], 16, v[94:95]
	v_lshl_add_u64 v[94:95], s[6:7], 0, v[94:95]
	v_cvt_pk_bf16_f32 v105, v96, v97
	global_store_dwordx4 v[118:119], v[102:105], off offset:256
	s_mov_b64 s[46:47], s[40:41]
	s_mov_b64 s[44:45], s[38:39]
	v_lshl_add_u64 v[102:103], v[94:95], 0, v[168:169]
	v_cvt_pk_bf16_f32 v94, v98, v99
	v_cvt_pk_bf16_f32 v95, v100, v101
	v_cvt_pk_bf16_f32 v96, v90, v91
	v_cvt_pk_bf16_f32 v97, v92, v93
	global_store_dwordx4 v[102:103], v[94:97], off
	v_cvt_pk_bf16_f32 v86, v86, v87
	v_cvt_pk_bf16_f32 v87, v88, v89
	v_cvt_pk_bf16_f32 v88, v78, v79
	v_or_b32_e32 v78, 48, v164
	v_ashrrev_i32_e32 v79, 31, v78
	v_lshlrev_b64 v[78:79], 16, v[78:79]
	v_lshl_add_u64 v[78:79], s[6:7], 0, v[78:79]
	v_cvt_pk_bf16_f32 v89, v80, v81
	global_store_dwordx4 v[102:103], v[86:89], off offset:256
	s_nop 1
	v_lshl_add_u64 v[86:87], v[78:79], 0, v[168:169]
	v_cvt_pk_bf16_f32 v78, v82, v83
	v_cvt_pk_bf16_f32 v79, v84, v85
	v_cvt_pk_bf16_f32 v80, v74, v75
	v_cvt_pk_bf16_f32 v81, v76, v77
	global_store_dwordx4 v[86:87], v[78:81], off
	v_cvt_pk_bf16_f32 v70, v70, v71
	v_cvt_pk_bf16_f32 v71, v72, v73
	v_cvt_pk_bf16_f32 v72, v66, v67
	v_cvt_pk_bf16_f32 v73, v68, v69
	global_store_dwordx4 v[86:87], v[70:73], off offset:256
	v_cvt_pk_bf16_f32 v62, v62, v63
	v_cvt_pk_bf16_f32 v63, v64, v65
	v_cvt_pk_bf16_f32 v64, v58, v59
	v_add_co_u32_e32 v58, vcc, s67, v148
	v_lshl_add_u64 v[66:67], v[148:149], 0, s[10:11]
	s_nop 0
	v_addc_co_u32_e32 v59, vcc, 0, v149, vcc
	v_cvt_pk_bf16_f32 v65, v60, v61
	global_store_dwordx4 v[58:59], v[62:65], off
	v_cvt_pk_bf16_f32 v50, v50, v51
	v_cvt_pk_bf16_f32 v51, v52, v53
	v_cvt_pk_bf16_f32 v52, v42, v43
	v_cvt_pk_bf16_f32 v53, v44, v45
	global_store_dwordx4 v[66:67], v[50:53], off offset:256
	v_cvt_pk_bf16_f32 v42, v54, v55
	v_cvt_pk_bf16_f32 v43, v56, v57
	v_cvt_pk_bf16_f32 v44, v46, v47
	v_add_co_u32_e32 v46, vcc, s68, v148
	s_nop 0
	v_lshl_add_u64 v[50:51], v[148:149], 0, s[16:17]
	v_addc_co_u32_e32 v47, vcc, 0, v149, vcc
	v_cvt_pk_bf16_f32 v45, v48, v49
	global_store_dwordx4 v[46:47], v[42:45], off
	v_cvt_pk_bf16_f32 v34, v34, v35
	v_cvt_pk_bf16_f32 v35, v36, v37
	v_cvt_pk_bf16_f32 v36, v26, v27
	v_cvt_pk_bf16_f32 v37, v28, v29
	global_store_dwordx4 v[50:51], v[34:37], off offset:256
	v_cvt_pk_bf16_f32 v26, v38, v39
	v_cvt_pk_bf16_f32 v27, v40, v41
	v_cvt_pk_bf16_f32 v28, v30, v31
	v_add_co_u32_e32 v30, vcc, s69, v148
	s_nop 0
	v_lshl_add_u64 v[34:35], v[148:149], 0, s[18:19]
	v_addc_co_u32_e32 v31, vcc, 0, v149, vcc
	v_cvt_pk_bf16_f32 v29, v32, v33
	global_store_dwordx4 v[30:31], v[26:29], off
	v_cvt_pk_bf16_f32 v18, v18, v19
	v_cvt_pk_bf16_f32 v19, v20, v21
	v_cvt_pk_bf16_f32 v20, v10, v11
	v_cvt_pk_bf16_f32 v21, v12, v13
	global_store_dwordx4 v[34:35], v[18:21], off offset:256
	v_cvt_pk_bf16_f32 v10, v22, v23
	v_cvt_pk_bf16_f32 v11, v24, v25
	v_cvt_pk_bf16_f32 v12, v14, v15
	v_add_co_u32_e32 v14, vcc, s70, v148
	s_nop 0
	v_lshl_add_u64 v[18:19], v[148:149], 0, s[24:25]
	v_addc_co_u32_e32 v15, vcc, 0, v149, vcc
	s_and_b64 vcc, exec, s[0:1]
	v_cvt_pk_bf16_f32 v13, v16, v17
	global_store_dwordx4 v[14:15], v[10:13], off
	v_cvt_pk_bf16_f32 v6, v6, v7
	v_cvt_pk_bf16_f32 v7, v8, v9
	v_cvt_pk_bf16_f32 v8, v2, v3
	v_cvt_pk_bf16_f32 v9, v4, v5
	global_store_dwordx4 v[18:19], v[6:9], off offset:256
	s_cbranch_vccz .LBB0_338
	s_waitcnt vmcnt(0)
	s_cmpk_gt_u32 s3, 0xff
	s_cbranch_scc1 .LBB0_349
	s_barrier

.LBB0_365:
	ds_read_b128 v[158:161], v150
	ds_read_b128 v[162:165], v150 offset:1024
	ds_read_b128 v[166:169], v150 offset:2048
	ds_read_b128 v[170:173], v150 offset:3072
	s_add_u32 s46, s44, 0xfff80080
	s_addc_u32 s47, s45, -1
	s_cmp_eq_u32 s76, 28
	s_cselect_b32 s51, s37, s47
	s_cselect_b32 s50, s72, s46
	s_cselect_b32 s47, s27, s75
	s_cselect_b32 s46, s73, s74
	v_lshl_add_u64 v[148:149], s[44:45], 0, v[138:139]
	s_add_i32 m0, s34, 0xc000
	ds_read_b128 v[174:177], v151
	ds_read_b128 v[182:185], v151 offset:2048
	ds_read_b128 v[190:193], v151 offset:4096
	ds_read_b128 v[204:207], v151 offset:6144
	ds_read_b128 v[178:181], v151 offset:1024
	ds_read_b128 v[186:189], v151 offset:3072
	ds_read_b128 v[194:197], v151 offset:5120
	ds_read_b128 v[208:211], v151 offset:7168
	global_load_lds_dwordx4 v[148:149], off
	v_lshl_add_u64 v[148:149], s[44:45], 0, v[140:141]
	s_add_i32 m0, s34, 0xe000
	s_nop 0
	global_load_lds_dwordx4 v[148:149], off
	s_waitcnt lgkmcnt(8)
	s_barrier
	s_setprio 1
	s_waitcnt lgkmcnt(7)
	v_mfma_f32_16x16x32_bf16 v[126:129], v[158:161], v[174:177], v[126:129]
	v_mfma_f32_16x16x32_bf16 v[122:125], v[166:169], v[174:177], v[122:125]
	s_waitcnt lgkmcnt(6)
	v_mfma_f32_16x16x32_bf16 v[114:117], v[158:161], v[182:185], v[114:117]
	v_mfma_f32_16x16x32_bf16 v[106:109], v[166:169], v[182:185], v[106:109]
	s_waitcnt lgkmcnt(5)
	v_mfma_f32_16x16x32_bf16 v[98:101], v[158:161], v[190:193], v[98:101]
	v_mfma_f32_16x16x32_bf16 v[90:93], v[166:169], v[190:193], v[90:93]
	s_waitcnt lgkmcnt(4)
	v_mfma_f32_16x16x32_bf16 v[82:85], v[158:161], v[204:207], v[82:85]
	v_mfma_f32_16x16x32_bf16 v[74:77], v[166:169], v[204:207], v[74:77]
	s_waitcnt lgkmcnt(3)
	v_mfma_f32_16x16x32_bf16 v[126:129], v[162:165], v[178:181], v[126:129]
	v_mfma_f32_16x16x32_bf16 v[122:125], v[170:173], v[178:181], v[122:125]
	s_waitcnt lgkmcnt(2)
	v_mfma_f32_16x16x32_bf16 v[114:117], v[162:165], v[186:189], v[114:117]
	v_mfma_f32_16x16x32_bf16 v[106:109], v[170:173], v[186:189], v[106:109]
	s_waitcnt lgkmcnt(1)
	v_mfma_f32_16x16x32_bf16 v[98:101], v[162:165], v[194:197], v[98:101]
	v_mfma_f32_16x16x32_bf16 v[90:93], v[170:173], v[194:197], v[90:93]
	s_waitcnt lgkmcnt(0)
	v_mfma_f32_16x16x32_bf16 v[82:85], v[162:165], v[208:211], v[82:85]
	v_mfma_f32_16x16x32_bf16 v[74:77], v[170:173], v[208:211], v[74:77]
	s_setprio 0
	s_barrier
	s_add_i32 s77, s65, s33
	v_lshl_add_u64 v[148:149], s[46:47], 0, v[132:133]
	s_mov_b32 m0, s77
	ds_read_b128 v[212:215], v152
	ds_read_b128 v[220:223], v152 offset:2048
	ds_read_b128 v[216:219], v152 offset:1024
	ds_read_b128 v[224:227], v152 offset:3072
	global_load_lds_dwordx4 v[148:149], off
	v_lshl_add_u64 v[198:199], s[46:47], 0, v[136:137]
	s_add_i32 m0, s77, 0x2000
	s_nop 0
	global_load_lds_dwordx4 v[198:199], off
	s_barrier
	s_setprio 1
	s_waitcnt lgkmcnt(2)
	v_mfma_f32_16x16x32_bf16 v[118:121], v[212:215], v[174:177], v[118:121]
	v_mfma_f32_16x16x32_bf16 v[110:113], v[220:223], v[174:177], v[110:113]
	v_mfma_f32_16x16x32_bf16 v[102:105], v[212:215], v[182:185], v[102:105]
	v_mfma_f32_16x16x32_bf16 v[94:97], v[220:223], v[182:185], v[94:97]
	v_mfma_f32_16x16x32_bf16 v[86:89], v[212:215], v[190:193], v[86:89]
	v_mfma_f32_16x16x32_bf16 v[78:81], v[220:223], v[190:193], v[78:81]
	v_mfma_f32_16x16x32_bf16 v[70:73], v[212:215], v[204:207], v[70:73]
	v_mfma_f32_16x16x32_bf16 v[66:69], v[220:223], v[204:207], v[66:69]
	s_waitcnt lgkmcnt(0)
	v_mfma_f32_16x16x32_bf16 v[118:121], v[216:219], v[178:181], v[118:121]
	v_mfma_f32_16x16x32_bf16 v[110:113], v[224:227], v[178:181], v[110:113]
	v_mfma_f32_16x16x32_bf16 v[102:105], v[216:219], v[186:189], v[102:105]
	v_mfma_f32_16x16x32_bf16 v[94:97], v[224:227], v[186:189], v[94:97]
	v_mfma_f32_16x16x32_bf16 v[86:89], v[216:219], v[194:197], v[86:89]
	v_mfma_f32_16x16x32_bf16 v[78:81], v[224:227], v[194:197], v[78:81]
	v_mfma_f32_16x16x32_bf16 v[70:73], v[216:219], v[208:211], v[70:73]
	v_mfma_f32_16x16x32_bf16 v[66:69], v[224:227], v[208:211], v[66:69]
	s_setprio 0
	s_mov_b32 m0, s34
	v_lshl_add_u64 v[228:229], s[50:51], 0, v[130:131]
	s_barrier
	ds_read_b128 v[174:177], v151 offset:16384
	ds_read_b128 v[182:185], v151 offset:18432
	ds_read_b128 v[190:193], v151 offset:20480
	ds_read_b128 v[204:207], v151 offset:22528
	ds_read_b128 v[178:181], v151 offset:17408
	ds_read_b128 v[186:189], v151 offset:19456
	ds_read_b128 v[194:197], v151 offset:21504
	ds_read_b128 v[208:211], v151 offset:23552
	global_load_lds_dwordx4 v[228:229], off
	v_lshl_add_u64 v[230:231], s[50:51], 0, v[134:135]
	s_mov_b32 m0, s35
	s_nop 0
	global_load_lds_dwordx4 v[230:231], off
	s_barrier
	s_setprio 1
	s_waitcnt lgkmcnt(7)
	v_mfma_f32_16x16x32_bf16 v[62:65], v[158:161], v[174:177], v[62:65]
	v_mfma_f32_16x16x32_bf16 v[58:61], v[166:169], v[174:177], v[58:61]
	s_waitcnt lgkmcnt(6)
	v_mfma_f32_16x16x32_bf16 v[54:57], v[158:161], v[182:185], v[54:57]
	v_mfma_f32_16x16x32_bf16 v[46:49], v[166:169], v[182:185], v[46:49]
	s_waitcnt lgkmcnt(5)
	v_mfma_f32_16x16x32_bf16 v[38:41], v[158:161], v[190:193], v[38:41]
	v_mfma_f32_16x16x32_bf16 v[30:33], v[166:169], v[190:193], v[30:33]
	s_waitcnt lgkmcnt(4)
	v_mfma_f32_16x16x32_bf16 v[22:25], v[158:161], v[204:207], v[22:25]
	v_mfma_f32_16x16x32_bf16 v[14:17], v[166:169], v[204:207], v[14:17]
	s_waitcnt lgkmcnt(3)
	v_mfma_f32_16x16x32_bf16 v[62:65], v[162:165], v[178:181], v[62:65]
	v_mfma_f32_16x16x32_bf16 v[58:61], v[170:173], v[178:181], v[58:61]
	s_waitcnt lgkmcnt(2)
	v_mfma_f32_16x16x32_bf16 v[54:57], v[162:165], v[186:189], v[54:57]
	v_mfma_f32_16x16x32_bf16 v[46:49], v[170:173], v[186:189], v[46:49]
	s_waitcnt lgkmcnt(1)
	v_mfma_f32_16x16x32_bf16 v[38:41], v[162:165], v[194:197], v[38:41]
	v_mfma_f32_16x16x32_bf16 v[30:33], v[170:173], v[194:197], v[30:33]
	s_waitcnt lgkmcnt(0)
	v_mfma_f32_16x16x32_bf16 v[22:25], v[162:165], v[208:211], v[22:25]
	v_mfma_f32_16x16x32_bf16 v[14:17], v[170:173], v[208:211], v[14:17]
	s_setprio 0
	s_barrier
	s_add_u32 s78, s46, 0x80000
	s_addc_u32 s79, s47, 0
	s_add_i32 s77, s66, s33
	v_lshl_add_u64 v[158:159], s[78:79], 0, v[132:133]
	s_mov_b32 m0, s77
	s_nop 0
	global_load_lds_dwordx4 v[158:159], off
	v_lshl_add_u64 v[158:159], s[78:79], 0, v[136:137]
	s_add_i32 m0, s77, 0x2000
	s_nop 0
	global_load_lds_dwordx4 v[158:159], off
	s_waitcnt vmcnt(6)
	s_barrier
	s_setprio 1
	v_mfma_f32_16x16x32_bf16 v[50:53], v[212:215], v[174:177], v[50:53]
	v_mfma_f32_16x16x32_bf16 v[42:45], v[220:223], v[174:177], v[42:45]
	v_mfma_f32_16x16x32_bf16 v[34:37], v[212:215], v[182:185], v[34:37]
	v_mfma_f32_16x16x32_bf16 v[26:29], v[220:223], v[182:185], v[26:29]
	v_mfma_f32_16x16x32_bf16 v[18:21], v[212:215], v[190:193], v[18:21]
	v_mfma_f32_16x16x32_bf16 v[10:13], v[220:223], v[190:193], v[10:13]
	v_mfma_f32_16x16x32_bf16 v[6:9], v[212:215], v[204:207], v[6:9]
	v_mfma_f32_16x16x32_bf16 v[2:5], v[220:223], v[204:207], v[2:5]
	v_mfma_f32_16x16x32_bf16 v[50:53], v[216:219], v[178:181], v[50:53]
	v_mfma_f32_16x16x32_bf16 v[42:45], v[224:227], v[178:181], v[42:45]
	v_mfma_f32_16x16x32_bf16 v[34:37], v[216:219], v[186:189], v[34:37]
	v_mfma_f32_16x16x32_bf16 v[26:29], v[224:227], v[186:189], v[26:29]
	v_mfma_f32_16x16x32_bf16 v[18:21], v[216:219], v[194:197], v[18:21]
	v_mfma_f32_16x16x32_bf16 v[10:13], v[224:227], v[194:197], v[10:13]
	v_mfma_f32_16x16x32_bf16 v[6:9], v[216:219], v[208:211], v[6:9]
	v_mfma_f32_16x16x32_bf16 v[2:5], v[224:227], v[208:211], v[2:5]
	s_setprio 0
	s_add_i32 s77, 0, 0x18000
	v_add_u32_e32 v153, s77, v155
	s_barrier
	ds_read_b128 v[158:161], v153
	ds_read_b128 v[162:165], v153 offset:1024
	ds_read_b128 v[166:169], v153 offset:2048
	ds_read_b128 v[170:173], v153 offset:3072
	s_add_u32 s50, s50, 0x80000
	s_addc_u32 s51, s51, 0
	s_mov_b32 m0, s43
	v_lshl_add_u64 v[212:213], s[50:51], 0, v[130:131]
	ds_read_b128 v[174:177], v151 offset:32768
	ds_read_b128 v[182:185], v151 offset:34816
	ds_read_b128 v[190:193], v151 offset:36864
	ds_read_b128 v[204:207], v151 offset:38912
	ds_read_b128 v[178:181], v151 offset:33792
	ds_read_b128 v[186:189], v151 offset:35840
	ds_read_b128 v[194:197], v151 offset:37888
	ds_read_b128 v[208:211], v151 offset:39936
	global_load_lds_dwordx4 v[212:213], off
	v_lshl_add_u64 v[212:213], s[50:51], 0, v[134:135]
	s_mov_b32 m0, s60
	s_nop 0
	global_load_lds_dwordx4 v[212:213], off
	s_waitcnt lgkmcnt(8)
	s_barrier
	s_setprio 1
	s_waitcnt lgkmcnt(7)
	v_mfma_f32_16x16x32_bf16 v[126:129], v[158:161], v[174:177], v[126:129]
	v_mfma_f32_16x16x32_bf16 v[122:125], v[166:169], v[174:177], v[122:125]
	s_waitcnt lgkmcnt(6)
	v_mfma_f32_16x16x32_bf16 v[114:117], v[158:161], v[182:185], v[114:117]
	v_mfma_f32_16x16x32_bf16 v[106:109], v[166:169], v[182:185], v[106:109]
	s_waitcnt lgkmcnt(5)
	v_mfma_f32_16x16x32_bf16 v[98:101], v[158:161], v[190:193], v[98:101]
	v_mfma_f32_16x16x32_bf16 v[90:93], v[166:169], v[190:193], v[90:93]
	s_waitcnt lgkmcnt(4)
	v_mfma_f32_16x16x32_bf16 v[82:85], v[158:161], v[204:207], v[82:85]
	v_mfma_f32_16x16x32_bf16 v[74:77], v[166:169], v[204:207], v[74:77]
	s_waitcnt lgkmcnt(3)
	v_mfma_f32_16x16x32_bf16 v[126:129], v[162:165], v[178:181], v[126:129]
	v_mfma_f32_16x16x32_bf16 v[122:125], v[170:173], v[178:181], v[122:125]
	s_waitcnt lgkmcnt(2)
	v_mfma_f32_16x16x32_bf16 v[114:117], v[162:165], v[186:189], v[114:117]
	v_mfma_f32_16x16x32_bf16 v[106:109], v[170:173], v[186:189], v[106:109]
	s_waitcnt lgkmcnt(1)
	v_mfma_f32_16x16x32_bf16 v[98:101], v[162:165], v[194:197], v[98:101]
	v_mfma_f32_16x16x32_bf16 v[90:93], v[170:173], v[194:197], v[90:93]
	s_waitcnt lgkmcnt(0)
	v_mfma_f32_16x16x32_bf16 v[82:85], v[162:165], v[208:211], v[82:85]
	v_mfma_f32_16x16x32_bf16 v[74:77], v[170:173], v[208:211], v[74:77]
	s_setprio 0
	s_barrier
	s_add_i32 s50, 0, 0x1c000
	s_add_i32 s51, s77, s33
	v_add_u32_e32 v153, s50, v155
	v_lshl_add_u64 v[148:149], v[148:149], 0, s[10:11]
	s_mov_b32 m0, s51
	ds_read_b128 v[212:215], v153
	ds_read_b128 v[220:223], v153 offset:2048
	ds_read_b128 v[216:219], v153 offset:1024
	ds_read_b128 v[224:227], v153 offset:3072
	global_load_lds_dwordx4 v[148:149], off
	v_lshl_add_u64 v[148:149], v[198:199], 0, s[10:11]
	s_add_i32 m0, s51, 0x2000
	s_nop 0
	global_load_lds_dwordx4 v[148:149], off
	s_barrier
	s_setprio 1
	s_waitcnt lgkmcnt(2)
	v_mfma_f32_16x16x32_bf16 v[118:121], v[212:215], v[174:177], v[118:121]
	v_mfma_f32_16x16x32_bf16 v[110:113], v[220:223], v[174:177], v[110:113]
	v_mfma_f32_16x16x32_bf16 v[102:105], v[212:215], v[182:185], v[102:105]
	v_mfma_f32_16x16x32_bf16 v[94:97], v[220:223], v[182:185], v[94:97]
	v_mfma_f32_16x16x32_bf16 v[86:89], v[212:215], v[190:193], v[86:89]
	v_mfma_f32_16x16x32_bf16 v[78:81], v[220:223], v[190:193], v[78:81]
	v_mfma_f32_16x16x32_bf16 v[70:73], v[212:215], v[204:207], v[70:73]
	v_mfma_f32_16x16x32_bf16 v[66:69], v[220:223], v[204:207], v[66:69]
	s_waitcnt lgkmcnt(0)
	v_mfma_f32_16x16x32_bf16 v[118:121], v[216:219], v[178:181], v[118:121]
	v_mfma_f32_16x16x32_bf16 v[110:113], v[224:227], v[178:181], v[110:113]
	v_mfma_f32_16x16x32_bf16 v[102:105], v[216:219], v[186:189], v[102:105]
	v_mfma_f32_16x16x32_bf16 v[94:97], v[224:227], v[186:189], v[94:97]
	v_mfma_f32_16x16x32_bf16 v[86:89], v[216:219], v[194:197], v[86:89]
	v_mfma_f32_16x16x32_bf16 v[78:81], v[224:227], v[194:197], v[78:81]
	v_mfma_f32_16x16x32_bf16 v[70:73], v[216:219], v[208:211], v[70:73]
	v_mfma_f32_16x16x32_bf16 v[66:69], v[224:227], v[208:211], v[66:69]
	s_setprio 0
	s_mov_b32 m0, s62
	v_lshl_add_u64 v[148:149], v[228:229], 0, s[10:11]
	s_barrier
	ds_read_b128 v[174:177], v151 offset:49152
	ds_read_b128 v[182:185], v151 offset:51200
	ds_read_b128 v[190:193], v151 offset:53248
	ds_read_b128 v[204:207], v151 offset:55296
	ds_read_b128 v[178:181], v151 offset:50176
	ds_read_b128 v[186:189], v151 offset:52224
	ds_read_b128 v[194:197], v151 offset:54272
	ds_read_b128 v[208:211], v151 offset:56320
	global_load_lds_dwordx4 v[148:149], off
	v_lshl_add_u64 v[148:149], v[230:231], 0, s[10:11]
	s_mov_b32 m0, s63
	s_nop 0
	global_load_lds_dwordx4 v[148:149], off
	s_barrier
	s_setprio 1
	s_waitcnt lgkmcnt(7)
	v_mfma_f32_16x16x32_bf16 v[62:65], v[158:161], v[174:177], v[62:65]
	v_mfma_f32_16x16x32_bf16 v[58:61], v[166:169], v[174:177], v[58:61]
	s_waitcnt lgkmcnt(6)
	v_mfma_f32_16x16x32_bf16 v[54:57], v[158:161], v[182:185], v[54:57]
	v_mfma_f32_16x16x32_bf16 v[46:49], v[166:169], v[182:185], v[46:49]
	s_waitcnt lgkmcnt(5)
	v_mfma_f32_16x16x32_bf16 v[38:41], v[158:161], v[190:193], v[38:41]
	v_mfma_f32_16x16x32_bf16 v[30:33], v[166:169], v[190:193], v[30:33]
	s_waitcnt lgkmcnt(4)
	v_mfma_f32_16x16x32_bf16 v[22:25], v[158:161], v[204:207], v[22:25]
	v_mfma_f32_16x16x32_bf16 v[14:17], v[166:169], v[204:207], v[14:17]
	s_waitcnt lgkmcnt(3)
	v_mfma_f32_16x16x32_bf16 v[62:65], v[162:165], v[178:181], v[62:65]
	v_mfma_f32_16x16x32_bf16 v[58:61], v[170:173], v[178:181], v[58:61]
	s_waitcnt lgkmcnt(2)
	v_mfma_f32_16x16x32_bf16 v[54:57], v[162:165], v[186:189], v[54:57]
	v_mfma_f32_16x16x32_bf16 v[46:49], v[170:173], v[186:189], v[46:49]
	s_waitcnt lgkmcnt(1)
	v_mfma_f32_16x16x32_bf16 v[38:41], v[162:165], v[194:197], v[38:41]
	v_mfma_f32_16x16x32_bf16 v[30:33], v[170:173], v[194:197], v[30:33]
	s_waitcnt lgkmcnt(0)
	v_mfma_f32_16x16x32_bf16 v[22:25], v[162:165], v[208:211], v[22:25]
	v_mfma_f32_16x16x32_bf16 v[14:17], v[170:173], v[208:211], v[14:17]
	s_setprio 0
	s_barrier
	s_add_u32 s46, s46, 0x80080
	s_addc_u32 s47, s47, 0
	s_add_i32 s50, s50, s33
	v_lshl_add_u64 v[148:149], s[46:47], 0, v[132:133]
	s_mov_b32 m0, s50
	s_nop 0
	global_load_lds_dwordx4 v[148:149], off
	v_lshl_add_u64 v[148:149], s[46:47], 0, v[136:137]
	s_add_i32 m0, s50, 0x2000
	s_nop 0
	global_load_lds_dwordx4 v[148:149], off
	s_waitcnt vmcnt(6)
	s_barrier
	s_setprio 1
	v_mfma_f32_16x16x32_bf16 v[50:53], v[212:215], v[174:177], v[50:53]
	v_mfma_f32_16x16x32_bf16 v[42:45], v[220:223], v[174:177], v[42:45]
	v_mfma_f32_16x16x32_bf16 v[34:37], v[212:215], v[182:185], v[34:37]
	v_mfma_f32_16x16x32_bf16 v[26:29], v[220:223], v[182:185], v[26:29]
	v_mfma_f32_16x16x32_bf16 v[18:21], v[212:215], v[190:193], v[18:21]
	v_mfma_f32_16x16x32_bf16 v[10:13], v[220:223], v[190:193], v[10:13]
	v_mfma_f32_16x16x32_bf16 v[6:9], v[212:215], v[204:207], v[6:9]
	v_mfma_f32_16x16x32_bf16 v[2:5], v[220:223], v[204:207], v[2:5]
	v_mfma_f32_16x16x32_bf16 v[50:53], v[216:219], v[178:181], v[50:53]
	v_mfma_f32_16x16x32_bf16 v[42:45], v[224:227], v[178:181], v[42:45]
	v_mfma_f32_16x16x32_bf16 v[34:37], v[216:219], v[186:189], v[34:37]
	v_mfma_f32_16x16x32_bf16 v[26:29], v[224:227], v[186:189], v[26:29]
	v_mfma_f32_16x16x32_bf16 v[18:21], v[216:219], v[194:197], v[18:21]
	v_mfma_f32_16x16x32_bf16 v[10:13], v[224:227], v[194:197], v[10:13]
	v_mfma_f32_16x16x32_bf16 v[6:9], v[216:219], v[208:211], v[6:9]
	v_mfma_f32_16x16x32_bf16 v[2:5], v[224:227], v[208:211], v[2:5]
	s_setprio 0
	s_add_i32 s76, s76, 2
	s_add_u32 s44, s44, 0x100
	s_addc_u32 s45, s45, 0
	s_add_u32 s74, s74, 0x100
	s_addc_u32 s75, s75, 0
	s_cmp_gt_u32 s76, 29
	s_barrier
	s_cbranch_scc0 .LBB0_365
	v_lshl_add_u32 v158, s42, 8, v157
	v_lshl_or_b32 v148, s71, 8, v154
	v_ashrrev_i32_e32 v159, 31, v158
	v_ashrrev_i32_e32 v149, 31, v148
	v_lshlrev_b64 v[160:161], 12, v[158:159]
	v_lshl_add_u64 v[160:161], s[8:9], 0, v[160:161]
	v_lshlrev_b64 v[162:163], 1, v[148:149]
	v_lshl_add_u64 v[148:149], v[160:161], 0, v[162:163]
	v_cvt_pk_bf16_f32 v126, v126, v127
	v_cvt_pk_bf16_f32 v127, v128, v129
	v_cvt_pk_bf16_f32 v128, v122, v123
	v_cvt_pk_bf16_f32 v129, v124, v125
	global_store_dwordx4 v[148:149], v[126:129], off
	v_cvt_pk_bf16_f32 v118, v118, v119
	v_cvt_pk_bf16_f32 v119, v120, v121
	v_cvt_pk_bf16_f32 v120, v110, v111
	v_or_b32_e32 v110, 16, v158
	v_ashrrev_i32_e32 v111, 31, v110
	v_lshlrev_b64 v[110:111], 12, v[110:111]
	v_lshl_add_u64 v[110:111], s[8:9], 0, v[110:111]
	v_cvt_pk_bf16_f32 v121, v112, v113
	global_store_dwordx4 v[148:149], v[118:121], off offset:256
	s_mov_b32 s71, s26
	s_mov_b32 s42, s36
	v_lshl_add_u64 v[118:119], v[110:111], 0, v[162:163]
	v_cvt_pk_bf16_f32 v110, v114, v115
	v_cvt_pk_bf16_f32 v111, v116, v117
	v_cvt_pk_bf16_f32 v112, v106, v107
	v_cvt_pk_bf16_f32 v113, v108, v109
	global_store_dwordx4 v[118:119], v[110:113], off
	v_cvt_pk_bf16_f32 v102, v102, v103
	v_cvt_pk_bf16_f32 v103, v104, v105
	v_cvt_pk_bf16_f32 v104, v94, v95
	v_or_b32_e32 v94, 32, v158
	v_ashrrev_i32_e32 v95, 31, v94
	v_lshlrev_b64 v[94:95], 12, v[94:95]
	v_lshl_add_u64 v[94:95], s[8:9], 0, v[94:95]
	v_cvt_pk_bf16_f32 v105, v96, v97
	global_store_dwordx4 v[118:119], v[102:105], off offset:256
	s_mov_b64 s[46:47], s[40:41]
	s_mov_b64 s[44:45], s[38:39]
	v_lshl_add_u64 v[102:103], v[94:95], 0, v[162:163]
	v_cvt_pk_bf16_f32 v94, v98, v99
	v_cvt_pk_bf16_f32 v95, v100, v101
	v_cvt_pk_bf16_f32 v96, v90, v91
	v_cvt_pk_bf16_f32 v97, v92, v93
	global_store_dwordx4 v[102:103], v[94:97], off
	v_cvt_pk_bf16_f32 v86, v86, v87
	v_cvt_pk_bf16_f32 v87, v88, v89
	v_cvt_pk_bf16_f32 v88, v78, v79
	v_or_b32_e32 v78, 48, v158
	v_ashrrev_i32_e32 v79, 31, v78
	v_lshlrev_b64 v[78:79], 12, v[78:79]
	v_lshl_add_u64 v[78:79], s[8:9], 0, v[78:79]
	v_cvt_pk_bf16_f32 v89, v80, v81
	global_store_dwordx4 v[102:103], v[86:89], off offset:256
	s_nop 1
	v_lshl_add_u64 v[86:87], v[78:79], 0, v[162:163]
	v_cvt_pk_bf16_f32 v78, v82, v83
	v_cvt_pk_bf16_f32 v79, v84, v85
	v_cvt_pk_bf16_f32 v80, v74, v75
	v_cvt_pk_bf16_f32 v81, v76, v77
	global_store_dwordx4 v[86:87], v[78:81], off
	v_cvt_pk_bf16_f32 v70, v70, v71
	v_cvt_pk_bf16_f32 v71, v72, v73
	v_cvt_pk_bf16_f32 v72, v66, v67
	v_cvt_pk_bf16_f32 v73, v68, v69
	global_store_dwordx4 v[86:87], v[70:73], off offset:256
	v_cvt_pk_bf16_f32 v62, v62, v63
	v_cvt_pk_bf16_f32 v63, v64, v65
	v_cvt_pk_bf16_f32 v64, v58, v59
	v_add_co_u32_e32 v58, vcc, s67, v148
	v_lshl_add_u64 v[66:67], v[148:149], 0, s[6:7]
	s_nop 0
	v_addc_co_u32_e32 v59, vcc, 0, v149, vcc
	v_cvt_pk_bf16_f32 v65, v60, v61
	global_store_dwordx4 v[58:59], v[62:65], off
	v_cvt_pk_bf16_f32 v50, v50, v51
	v_cvt_pk_bf16_f32 v51, v52, v53
	v_cvt_pk_bf16_f32 v52, v42, v43
	v_cvt_pk_bf16_f32 v53, v44, v45
	global_store_dwordx4 v[66:67], v[50:53], off offset:256
	v_cvt_pk_bf16_f32 v42, v54, v55
	v_cvt_pk_bf16_f32 v43, v56, v57
	v_cvt_pk_bf16_f32 v44, v46, v47
	v_add_co_u32_e32 v46, vcc, s68, v148
	s_nop 0
	v_lshl_add_u64 v[50:51], v[148:149], 0, s[16:17]
	v_addc_co_u32_e32 v47, vcc, 0, v149, vcc
	v_cvt_pk_bf16_f32 v45, v48, v49
	global_store_dwordx4 v[46:47], v[42:45], off
	v_cvt_pk_bf16_f32 v34, v34, v35
	v_cvt_pk_bf16_f32 v35, v36, v37
	v_cvt_pk_bf16_f32 v36, v26, v27
	v_cvt_pk_bf16_f32 v37, v28, v29
	global_store_dwordx4 v[50:51], v[34:37], off offset:256
	v_cvt_pk_bf16_f32 v26, v38, v39
	v_cvt_pk_bf16_f32 v27, v40, v41
	v_cvt_pk_bf16_f32 v28, v30, v31
	v_add_co_u32_e32 v30, vcc, s69, v148
	s_nop 0
	v_lshl_add_u64 v[34:35], v[148:149], 0, s[18:19]
	v_addc_co_u32_e32 v31, vcc, 0, v149, vcc
	v_cvt_pk_bf16_f32 v29, v32, v33
	global_store_dwordx4 v[30:31], v[26:29], off
	v_cvt_pk_bf16_f32 v18, v18, v19
	v_cvt_pk_bf16_f32 v19, v20, v21
	v_cvt_pk_bf16_f32 v20, v10, v11
	v_cvt_pk_bf16_f32 v21, v12, v13
	global_store_dwordx4 v[34:35], v[18:21], off offset:256
	v_cvt_pk_bf16_f32 v10, v22, v23
	v_cvt_pk_bf16_f32 v11, v24, v25
	v_cvt_pk_bf16_f32 v12, v14, v15
	v_add_co_u32_e32 v14, vcc, s70, v148
	s_nop 0
	v_lshl_add_u64 v[18:19], v[148:149], 0, s[24:25]
	v_addc_co_u32_e32 v15, vcc, 0, v149, vcc
	s_and_b64 vcc, exec, s[0:1]
	v_cvt_pk_bf16_f32 v13, v16, v17
	global_store_dwordx4 v[14:15], v[10:13], off
	v_cvt_pk_bf16_f32 v6, v6, v7
	v_cvt_pk_bf16_f32 v7, v8, v9
	v_cvt_pk_bf16_f32 v8, v2, v3
	v_cvt_pk_bf16_f32 v9, v4, v5
	global_store_dwordx4 v[18:19], v[6:9], off offset:256
	s_cbranch_vccz .LBB0_358
	s_waitcnt vmcnt(0)
	s_cmpk_gt_u32 s3, 0xff
	s_cbranch_scc1 .LBB0_369
	s_barrier

.LBB0_710:
	s_add_u32 s44, s42, 0xfffe0080
	s_addc_u32 s45, s43, -1
	s_add_i32 s76, 0, 0x10000
	v_add_u32_e32 v142, s76, v177
	ds_read_b128 v[130:133], v142
	ds_read_b128 v[134:137], v142 offset:1024
	ds_read_b128 v[138:141], v142 offset:2048
	ds_read_b128 v[142:145], v142 offset:3072
	s_cmp_eq_u32 s75, 4
	s_cselect_b32 s47, s27, s45
	s_cselect_b32 s46, s41, s44
	s_cselect_b32 s45, s25, s74
	s_cselect_b32 s44, s72, s73
	v_lshl_add_u64 v[198:199], s[42:43], 0, v[158:159]
	s_add_i32 m0, s66, 0xc000
	ds_read_b128 v[166:169], v156
	ds_read_b128 v[182:185], v156 offset:2048
	ds_read_b128 v[190:193], v156 offset:4096
	ds_read_b128 v[202:205], v156 offset:6144
	ds_read_b128 v[178:181], v156 offset:1024
	ds_read_b128 v[186:189], v156 offset:3072
	ds_read_b128 v[194:197], v156 offset:5120
	ds_read_b128 v[206:209], v156 offset:7168
	global_load_lds_dwordx4 v[198:199], off
	v_lshl_add_u64 v[198:199], s[42:43], 0, v[160:161]
	s_add_i32 m0, s66, 0xe000
	s_nop 0
	global_load_lds_dwordx4 v[198:199], off
	s_waitcnt lgkmcnt(8)
	s_barrier
	s_setprio 1
	s_waitcnt lgkmcnt(7)
	v_mfma_f32_16x16x32_bf16 v[126:129], v[130:133], v[166:169], v[126:129]
	v_mfma_f32_16x16x32_bf16 v[122:125], v[138:141], v[166:169], v[122:125]
	s_waitcnt lgkmcnt(6)
	v_mfma_f32_16x16x32_bf16 v[110:113], v[130:133], v[182:185], v[110:113]
	v_mfma_f32_16x16x32_bf16 v[106:109], v[138:141], v[182:185], v[106:109]
	s_waitcnt lgkmcnt(5)
	v_mfma_f32_16x16x32_bf16 v[94:97], v[130:133], v[190:193], v[94:97]
	v_mfma_f32_16x16x32_bf16 v[90:93], v[138:141], v[190:193], v[90:93]
	s_waitcnt lgkmcnt(4)
	v_mfma_f32_16x16x32_bf16 v[78:81], v[130:133], v[202:205], v[78:81]
	v_mfma_f32_16x16x32_bf16 v[74:77], v[138:141], v[202:205], v[74:77]
	s_waitcnt lgkmcnt(3)
	v_mfma_f32_16x16x32_bf16 v[126:129], v[134:137], v[178:181], v[126:129]
	v_mfma_f32_16x16x32_bf16 v[122:125], v[142:145], v[178:181], v[122:125]
	s_waitcnt lgkmcnt(2)
	v_mfma_f32_16x16x32_bf16 v[110:113], v[134:137], v[186:189], v[110:113]
	v_mfma_f32_16x16x32_bf16 v[106:109], v[142:145], v[186:189], v[106:109]
	s_waitcnt lgkmcnt(1)
	v_mfma_f32_16x16x32_bf16 v[94:97], v[134:137], v[194:197], v[94:97]
	v_mfma_f32_16x16x32_bf16 v[90:93], v[142:145], v[194:197], v[90:93]
	s_waitcnt lgkmcnt(0)
	v_mfma_f32_16x16x32_bf16 v[78:81], v[134:137], v[206:209], v[78:81]
	v_mfma_f32_16x16x32_bf16 v[74:77], v[142:145], v[206:209], v[74:77]
	s_setprio 0
	s_barrier
	s_add_i32 s78, 0, 0x14000
	v_add_u32_e32 v198, s78, v177
	s_add_i32 s76, s76, s65
	ds_read_b128 v[210:213], v198
	ds_read_b128 v[218:221], v198 offset:2048
	ds_read_b128 v[214:217], v198 offset:1024
	ds_read_b128 v[222:225], v198 offset:3072
	v_lshl_add_u64 v[198:199], s[44:45], 0, v[150:151]
	s_mov_b32 m0, s76
	v_lshl_add_u64 v[226:227], s[44:45], 0, v[154:155]
	global_load_lds_dwordx4 v[198:199], off
	s_add_i32 m0, s76, 0x2000
	s_nop 0
	global_load_lds_dwordx4 v[226:227], off
	s_barrier
	s_setprio 1
	s_waitcnt lgkmcnt(2)
	v_mfma_f32_16x16x32_bf16 v[118:121], v[210:213], v[166:169], v[118:121]
	v_mfma_f32_16x16x32_bf16 v[114:117], v[218:221], v[166:169], v[114:117]
	v_mfma_f32_16x16x32_bf16 v[102:105], v[210:213], v[182:185], v[102:105]
	v_mfma_f32_16x16x32_bf16 v[98:101], v[218:221], v[182:185], v[98:101]
	v_mfma_f32_16x16x32_bf16 v[86:89], v[210:213], v[190:193], v[86:89]
	v_mfma_f32_16x16x32_bf16 v[82:85], v[218:221], v[190:193], v[82:85]
	v_mfma_f32_16x16x32_bf16 v[70:73], v[210:213], v[202:205], v[70:73]
	v_mfma_f32_16x16x32_bf16 v[66:69], v[218:221], v[202:205], v[66:69]
	s_waitcnt lgkmcnt(0)
	v_mfma_f32_16x16x32_bf16 v[118:121], v[214:217], v[178:181], v[118:121]
	v_mfma_f32_16x16x32_bf16 v[114:117], v[222:225], v[178:181], v[114:117]
	v_mfma_f32_16x16x32_bf16 v[102:105], v[214:217], v[186:189], v[102:105]
	v_mfma_f32_16x16x32_bf16 v[98:101], v[222:225], v[186:189], v[98:101]
	v_mfma_f32_16x16x32_bf16 v[86:89], v[214:217], v[194:197], v[86:89]
	v_mfma_f32_16x16x32_bf16 v[82:85], v[222:225], v[194:197], v[82:85]
	v_mfma_f32_16x16x32_bf16 v[70:73], v[214:217], v[206:209], v[70:73]
	v_mfma_f32_16x16x32_bf16 v[66:69], v[222:225], v[206:209], v[66:69]
	s_setprio 0
	s_mov_b32 m0, s66
	v_lshl_add_u64 v[228:229], s[46:47], 0, v[148:149]
	s_barrier
	ds_read_b128 v[166:169], v156 offset:16384
	ds_read_b128 v[182:185], v156 offset:18432
	ds_read_b128 v[190:193], v156 offset:20480
	ds_read_b128 v[202:205], v156 offset:22528
	ds_read_b128 v[178:181], v156 offset:17408
	ds_read_b128 v[186:189], v156 offset:19456
	ds_read_b128 v[194:197], v156 offset:21504
	ds_read_b128 v[206:209], v156 offset:23552
	global_load_lds_dwordx4 v[228:229], off
	v_lshl_add_u64 v[230:231], s[46:47], 0, v[152:153]
	s_mov_b32 m0, s67
	s_nop 0
	global_load_lds_dwordx4 v[230:231], off
	s_barrier
	s_setprio 1
	s_waitcnt lgkmcnt(7)
	v_mfma_f32_16x16x32_bf16 v[62:65], v[130:133], v[166:169], v[62:65]
	v_mfma_f32_16x16x32_bf16 v[58:61], v[138:141], v[166:169], v[58:61]
	s_waitcnt lgkmcnt(6)
	v_mfma_f32_16x16x32_bf16 v[46:49], v[130:133], v[182:185], v[46:49]
	v_mfma_f32_16x16x32_bf16 v[42:45], v[138:141], v[182:185], v[42:45]
	s_waitcnt lgkmcnt(5)
	v_mfma_f32_16x16x32_bf16 v[30:33], v[130:133], v[190:193], v[30:33]
	v_mfma_f32_16x16x32_bf16 v[26:29], v[138:141], v[190:193], v[26:29]
	s_waitcnt lgkmcnt(4)
	v_mfma_f32_16x16x32_bf16 v[14:17], v[130:133], v[202:205], v[14:17]
	v_mfma_f32_16x16x32_bf16 v[10:13], v[138:141], v[202:205], v[10:13]
	s_waitcnt lgkmcnt(3)
	v_mfma_f32_16x16x32_bf16 v[62:65], v[134:137], v[178:181], v[62:65]
	v_mfma_f32_16x16x32_bf16 v[58:61], v[142:145], v[178:181], v[58:61]
	s_waitcnt lgkmcnt(2)
	v_mfma_f32_16x16x32_bf16 v[46:49], v[134:137], v[186:189], v[46:49]
	v_mfma_f32_16x16x32_bf16 v[42:45], v[142:145], v[186:189], v[42:45]
	s_waitcnt lgkmcnt(1)
	v_mfma_f32_16x16x32_bf16 v[30:33], v[134:137], v[194:197], v[30:33]
	v_mfma_f32_16x16x32_bf16 v[26:29], v[142:145], v[194:197], v[26:29]
	s_waitcnt lgkmcnt(0)
	v_mfma_f32_16x16x32_bf16 v[14:17], v[134:137], v[206:209], v[14:17]
	v_mfma_f32_16x16x32_bf16 v[10:13], v[142:145], v[206:209], v[10:13]
	s_setprio 0
	s_barrier
	s_add_u32 s76, s44, 0x20000
	s_addc_u32 s77, s45, 0
	s_add_i32 s78, s78, s65
	v_lshl_add_u64 v[130:131], s[76:77], 0, v[150:151]
	s_mov_b32 m0, s78
	s_nop 0
	global_load_lds_dwordx4 v[130:131], off
	v_lshl_add_u64 v[130:131], s[76:77], 0, v[154:155]
	s_add_i32 m0, s78, 0x2000
	s_nop 0
	global_load_lds_dwordx4 v[130:131], off
	s_waitcnt vmcnt(6)
	s_barrier
	s_setprio 1
	v_mfma_f32_16x16x32_bf16 v[54:57], v[210:213], v[166:169], v[54:57]
	v_mfma_f32_16x16x32_bf16 v[50:53], v[218:221], v[166:169], v[50:53]
	v_mfma_f32_16x16x32_bf16 v[38:41], v[210:213], v[182:185], v[38:41]
	v_mfma_f32_16x16x32_bf16 v[34:37], v[218:221], v[182:185], v[34:37]
	v_mfma_f32_16x16x32_bf16 v[22:25], v[210:213], v[190:193], v[22:25]
	v_mfma_f32_16x16x32_bf16 v[18:21], v[218:221], v[190:193], v[18:21]
	v_mfma_f32_16x16x32_bf16 v[6:9], v[210:213], v[202:205], v[6:9]
	v_mfma_f32_16x16x32_bf16 v[2:5], v[218:221], v[202:205], v[2:5]
	v_mfma_f32_16x16x32_bf16 v[54:57], v[214:217], v[178:181], v[54:57]
	v_mfma_f32_16x16x32_bf16 v[50:53], v[222:225], v[178:181], v[50:53]
	v_mfma_f32_16x16x32_bf16 v[38:41], v[214:217], v[186:189], v[38:41]
	v_mfma_f32_16x16x32_bf16 v[34:37], v[222:225], v[186:189], v[34:37]
	v_mfma_f32_16x16x32_bf16 v[22:25], v[214:217], v[194:197], v[22:25]
	v_mfma_f32_16x16x32_bf16 v[18:21], v[222:225], v[194:197], v[18:21]
	v_mfma_f32_16x16x32_bf16 v[6:9], v[214:217], v[206:209], v[6:9]
	v_mfma_f32_16x16x32_bf16 v[2:5], v[222:225], v[206:209], v[2:5]
	s_setprio 0
	s_add_i32 s76, 0, 0x18000
	v_add_u32_e32 v142, s76, v177
	s_barrier
	ds_read_b128 v[130:133], v142
	ds_read_b128 v[134:137], v142 offset:1024
	ds_read_b128 v[138:141], v142 offset:2048
	ds_read_b128 v[142:145], v142 offset:3072
	s_add_u32 s46, s46, 0x20000
	s_addc_u32 s47, s47, 0
	s_mov_b32 m0, s68
	v_lshl_add_u64 v[210:211], s[46:47], 0, v[148:149]
	ds_read_b128 v[166:169], v156 offset:32768
	ds_read_b128 v[182:185], v156 offset:34816
	ds_read_b128 v[190:193], v156 offset:36864
	ds_read_b128 v[202:205], v156 offset:38912
	ds_read_b128 v[178:181], v156 offset:33792
	ds_read_b128 v[186:189], v156 offset:35840
	ds_read_b128 v[194:197], v156 offset:37888
	ds_read_b128 v[206:209], v156 offset:39936
	global_load_lds_dwordx4 v[210:211], off
	v_lshl_add_u64 v[210:211], s[46:47], 0, v[152:153]
	s_mov_b32 m0, s69
	s_nop 0
	global_load_lds_dwordx4 v[210:211], off
	s_waitcnt lgkmcnt(8)
	s_barrier
	s_setprio 1
	s_waitcnt lgkmcnt(7)
	v_mfma_f32_16x16x32_bf16 v[126:129], v[130:133], v[166:169], v[126:129]
	v_mfma_f32_16x16x32_bf16 v[122:125], v[138:141], v[166:169], v[122:125]
	s_waitcnt lgkmcnt(6)
	v_mfma_f32_16x16x32_bf16 v[110:113], v[130:133], v[182:185], v[110:113]
	v_mfma_f32_16x16x32_bf16 v[106:109], v[138:141], v[182:185], v[106:109]
	s_waitcnt lgkmcnt(5)
	v_mfma_f32_16x16x32_bf16 v[94:97], v[130:133], v[190:193], v[94:97]
	v_mfma_f32_16x16x32_bf16 v[90:93], v[138:141], v[190:193], v[90:93]
	s_waitcnt lgkmcnt(4)
	v_mfma_f32_16x16x32_bf16 v[78:81], v[130:133], v[202:205], v[78:81]
	v_mfma_f32_16x16x32_bf16 v[74:77], v[138:141], v[202:205], v[74:77]
	s_waitcnt lgkmcnt(3)
	v_mfma_f32_16x16x32_bf16 v[126:129], v[134:137], v[178:181], v[126:129]
	v_mfma_f32_16x16x32_bf16 v[122:125], v[142:145], v[178:181], v[122:125]
	s_waitcnt lgkmcnt(2)
	v_mfma_f32_16x16x32_bf16 v[110:113], v[134:137], v[186:189], v[110:113]
	v_mfma_f32_16x16x32_bf16 v[106:109], v[142:145], v[186:189], v[106:109]
	s_waitcnt lgkmcnt(1)
	v_mfma_f32_16x16x32_bf16 v[94:97], v[134:137], v[194:197], v[94:97]
	v_mfma_f32_16x16x32_bf16 v[90:93], v[142:145], v[194:197], v[90:93]
	s_waitcnt lgkmcnt(0)
	v_mfma_f32_16x16x32_bf16 v[78:81], v[134:137], v[206:209], v[78:81]
	v_mfma_f32_16x16x32_bf16 v[74:77], v[142:145], v[206:209], v[74:77]
	s_setprio 0
	s_barrier
	s_add_i32 s46, 0, 0x1c000
	s_add_i32 s47, s76, s65
	v_add_u32_e32 v201, s46, v177
	v_lshl_add_u64 v[198:199], v[198:199], 0, s[16:17]
	s_mov_b32 m0, s47
	ds_read_b128 v[210:213], v201
	ds_read_b128 v[218:221], v201 offset:2048
	ds_read_b128 v[214:217], v201 offset:1024
	ds_read_b128 v[222:225], v201 offset:3072
	global_load_lds_dwordx4 v[198:199], off
	v_lshl_add_u64 v[198:199], v[226:227], 0, s[16:17]
	s_add_i32 m0, s47, 0x2000
	s_nop 0
	global_load_lds_dwordx4 v[198:199], off
	s_barrier
	s_setprio 1
	s_waitcnt lgkmcnt(2)
	v_mfma_f32_16x16x32_bf16 v[118:121], v[210:213], v[166:169], v[118:121]
	v_mfma_f32_16x16x32_bf16 v[114:117], v[218:221], v[166:169], v[114:117]
	v_mfma_f32_16x16x32_bf16 v[102:105], v[210:213], v[182:185], v[102:105]
	v_mfma_f32_16x16x32_bf16 v[98:101], v[218:221], v[182:185], v[98:101]
	v_mfma_f32_16x16x32_bf16 v[86:89], v[210:213], v[190:193], v[86:89]
	v_mfma_f32_16x16x32_bf16 v[82:85], v[218:221], v[190:193], v[82:85]
	v_mfma_f32_16x16x32_bf16 v[70:73], v[210:213], v[202:205], v[70:73]
	v_mfma_f32_16x16x32_bf16 v[66:69], v[218:221], v[202:205], v[66:69]
	s_waitcnt lgkmcnt(0)
	v_mfma_f32_16x16x32_bf16 v[118:121], v[214:217], v[178:181], v[118:121]
	v_mfma_f32_16x16x32_bf16 v[114:117], v[222:225], v[178:181], v[114:117]
	v_mfma_f32_16x16x32_bf16 v[102:105], v[214:217], v[186:189], v[102:105]
	v_mfma_f32_16x16x32_bf16 v[98:101], v[222:225], v[186:189], v[98:101]
	v_mfma_f32_16x16x32_bf16 v[86:89], v[214:217], v[194:197], v[86:89]
	v_mfma_f32_16x16x32_bf16 v[82:85], v[222:225], v[194:197], v[82:85]
	v_mfma_f32_16x16x32_bf16 v[70:73], v[214:217], v[206:209], v[70:73]
	v_mfma_f32_16x16x32_bf16 v[66:69], v[222:225], v[206:209], v[66:69]
	s_setprio 0
	s_mov_b32 m0, s70
	v_lshl_add_u64 v[198:199], v[228:229], 0, s[16:17]
	s_barrier
	ds_read_b128 v[166:169], v156 offset:49152
	ds_read_b128 v[182:185], v156 offset:51200
	ds_read_b128 v[190:193], v156 offset:53248
	ds_read_b128 v[202:205], v156 offset:55296
	ds_read_b128 v[178:181], v156 offset:50176
	ds_read_b128 v[186:189], v156 offset:52224
	ds_read_b128 v[194:197], v156 offset:54272
	ds_read_b128 v[206:209], v156 offset:56320
	global_load_lds_dwordx4 v[198:199], off
	v_lshl_add_u64 v[198:199], v[230:231], 0, s[16:17]
	s_mov_b32 m0, s71
	s_nop 0
	global_load_lds_dwordx4 v[198:199], off
	s_barrier
	s_setprio 1
	s_waitcnt lgkmcnt(7)
	v_mfma_f32_16x16x32_bf16 v[62:65], v[130:133], v[166:169], v[62:65]
	v_mfma_f32_16x16x32_bf16 v[58:61], v[138:141], v[166:169], v[58:61]
	s_waitcnt lgkmcnt(6)
	v_mfma_f32_16x16x32_bf16 v[46:49], v[130:133], v[182:185], v[46:49]
	v_mfma_f32_16x16x32_bf16 v[42:45], v[138:141], v[182:185], v[42:45]
	s_waitcnt lgkmcnt(5)
	v_mfma_f32_16x16x32_bf16 v[30:33], v[130:133], v[190:193], v[30:33]
	v_mfma_f32_16x16x32_bf16 v[26:29], v[138:141], v[190:193], v[26:29]
	s_waitcnt lgkmcnt(4)
	v_mfma_f32_16x16x32_bf16 v[14:17], v[130:133], v[202:205], v[14:17]
	v_mfma_f32_16x16x32_bf16 v[10:13], v[138:141], v[202:205], v[10:13]
	s_waitcnt lgkmcnt(3)
	v_mfma_f32_16x16x32_bf16 v[62:65], v[134:137], v[178:181], v[62:65]
	v_mfma_f32_16x16x32_bf16 v[58:61], v[142:145], v[178:181], v[58:61]
	s_waitcnt lgkmcnt(2)
	v_mfma_f32_16x16x32_bf16 v[46:49], v[134:137], v[186:189], v[46:49]
	v_mfma_f32_16x16x32_bf16 v[42:45], v[142:145], v[186:189], v[42:45]
	s_waitcnt lgkmcnt(1)
	v_mfma_f32_16x16x32_bf16 v[30:33], v[134:137], v[194:197], v[30:33]
	v_mfma_f32_16x16x32_bf16 v[26:29], v[142:145], v[194:197], v[26:29]
	s_waitcnt lgkmcnt(0)
	v_mfma_f32_16x16x32_bf16 v[14:17], v[134:137], v[206:209], v[14:17]
	v_mfma_f32_16x16x32_bf16 v[10:13], v[142:145], v[206:209], v[10:13]
	s_setprio 0
	s_barrier
	s_add_u32 s44, s44, 0x20080
	s_addc_u32 s45, s45, 0
	s_add_i32 s46, s46, s65
	v_lshl_add_u64 v[130:131], s[44:45], 0, v[150:151]
	s_mov_b32 m0, s46
	s_nop 0
	global_load_lds_dwordx4 v[130:131], off
	v_lshl_add_u64 v[130:131], s[44:45], 0, v[154:155]
	s_add_i32 m0, s46, 0x2000
	s_nop 0
	global_load_lds_dwordx4 v[130:131], off
	s_waitcnt vmcnt(6)
	s_barrier
	s_setprio 1
	v_mfma_f32_16x16x32_bf16 v[54:57], v[210:213], v[166:169], v[54:57]
	v_mfma_f32_16x16x32_bf16 v[50:53], v[218:221], v[166:169], v[50:53]
	v_mfma_f32_16x16x32_bf16 v[38:41], v[210:213], v[182:185], v[38:41]
	v_mfma_f32_16x16x32_bf16 v[34:37], v[218:221], v[182:185], v[34:37]
	v_mfma_f32_16x16x32_bf16 v[22:25], v[210:213], v[190:193], v[22:25]
	v_mfma_f32_16x16x32_bf16 v[18:21], v[218:221], v[190:193], v[18:21]
	v_mfma_f32_16x16x32_bf16 v[6:9], v[210:213], v[202:205], v[6:9]
	v_mfma_f32_16x16x32_bf16 v[2:5], v[218:221], v[202:205], v[2:5]
	v_mfma_f32_16x16x32_bf16 v[54:57], v[214:217], v[178:181], v[54:57]
	v_mfma_f32_16x16x32_bf16 v[50:53], v[222:225], v[178:181], v[50:53]
	v_mfma_f32_16x16x32_bf16 v[38:41], v[214:217], v[186:189], v[38:41]
	v_mfma_f32_16x16x32_bf16 v[34:37], v[222:225], v[186:189], v[34:37]
	v_mfma_f32_16x16x32_bf16 v[22:25], v[214:217], v[194:197], v[22:25]
	v_mfma_f32_16x16x32_bf16 v[18:21], v[222:225], v[194:197], v[18:21]
	v_mfma_f32_16x16x32_bf16 v[6:9], v[214:217], v[206:209], v[6:9]
	v_mfma_f32_16x16x32_bf16 v[2:5], v[222:225], v[206:209], v[2:5]
	s_setprio 0
	s_add_i32 s75, s75, 2
	s_add_u32 s42, s42, 0x100
	s_addc_u32 s43, s43, 0
	s_add_u32 s73, s73, 0x100
	s_addc_u32 s74, s74, 0
	s_cmp_gt_u32 s75, 5
	s_barrier
	s_cbranch_scc0 .LBB0_710
	global_load_dwordx4 v[138:141], v[162:163], off offset:16
	global_load_dwordx4 v[142:145], v[162:163], off
	global_load_dwordx4 v[130:133], v[162:163], off offset:528
	global_load_dwordx4 v[134:137], v[162:163], off offset:512
	s_cmp_lt_i32 s40, 48
	s_cselect_b32 s25, s50, 0xffffd000
	s_cselect_b32 s41, 0x4000, s49
	s_cmp_lt_i32 s40, 32
	s_cselect_b64 vcc, -1, 0
	s_and_b64 s[42:43], vcc, exec
	s_cselect_b32 s42, 0, s25
	v_lshl_add_u32 v167, s40, 8, v176
	v_add_u32_e32 v178, s42, v167
	v_cndmask_b32_e32 v166, v174, v175, vcc
	v_cmp_ne_u32_e32 vcc, 0, v178
	s_cselect_b32 s27, s48, 0x2000
	s_cselect_b32 s25, 0, s41
	v_mov_b32_e32 v168, v166
	v_mov_b32_e32 v169, v166
	s_or_b64 s[46:47], s[20:21], vcc
	s_mov_b64 s[40:41], 0
	s_mov_b64 s[44:45], 0
	s_and_saveexec_b64 s[42:43], s[46:47]
	s_cbranch_execz .LBB0_713
	v_sub_u32_e32 v167, s27, v178
	v_cndmask_b32_e64 v167, v178, v167, s[4:5]
	v_add_u32_e32 v180, s25, v167
	v_ashrrev_i32_e32 v181, 31, v180
	v_lshlrev_b64 v[180:181], 11, v[180:181]
	v_mov_b32_e32 v167, v166
	v_lshl_add_u64 v[180:181], v[164:165], 0, v[180:181]
	s_waitcnt vmcnt(0)
	v_pk_fma_f32 v[128:129], v[166:167], v[128:129], v[144:145]
	v_pk_fma_f32 v[126:127], v[168:169], v[126:127], v[142:143]
	v_pk_fma_f32 v[182:183], v[166:167], v[124:125], v[140:141]
	v_pk_fma_f32 v[124:125], v[168:169], v[122:123], v[138:139]
	v_cvt_pk_bf16_f32 v122, v126, v127
	v_cvt_pk_bf16_f32 v123, v128, v129
	s_and_b64 s[44:45], s[0:1], exec
	v_cvt_pk_bf16_f32 v124, v124, v125
	v_cvt_pk_bf16_f32 v125, v182, v183
	global_store_dwordx4 v[180:181], v[122:125], off
	v_pk_fma_f32 v[120:121], v[166:167], v[120:121], v[136:137]
	v_pk_fma_f32 v[118:119], v[168:169], v[118:119], v[134:135]
	v_pk_fma_f32 v[122:123], v[166:167], v[116:117], v[132:133]
	v_pk_fma_f32 v[116:117], v[168:169], v[114:115], v[130:131]
	v_cvt_pk_bf16_f32 v114, v118, v119
	v_cvt_pk_bf16_f32 v115, v120, v121
	s_nop 0
	v_cvt_pk_bf16_f32 v116, v116, v117
	v_cvt_pk_bf16_f32 v117, v122, v123
	global_store_dwordx4 v[180:181], v[114:117], off offset:256

.LBB0_909:
	ds_read_b128 v[154:157], v151
	ds_read_b128 v[158:161], v151 offset:1024
	ds_read_b128 v[162:165], v151 offset:2048
	ds_read_b128 v[166:169], v151 offset:3072
	s_add_u32 s42, s40, 0xfff80080
	s_addc_u32 s43, s41, -1
	s_cmp_eq_u32 s70, 28
	s_cselect_b32 s45, s25, s43
	s_cselect_b32 s44, s66, s42
	s_cselect_b32 s43, s23, s69
	s_cselect_b32 s42, s67, s68
	v_lshl_add_u64 v[148:149], s[40:41], 0, v[138:139]
	s_add_i32 m0, s34, 0xc000
	ds_read_b128 v[170:173], v152
	ds_read_b128 v[178:181], v152 offset:2048
	ds_read_b128 v[186:189], v152 offset:4096
	ds_read_b128 v[194:197], v152 offset:6144
	ds_read_b128 v[174:177], v152 offset:1024
	ds_read_b128 v[182:185], v152 offset:3072
	ds_read_b128 v[190:193], v152 offset:5120
	ds_read_b128 v[198:201], v152 offset:7168
	global_load_lds_dwordx4 v[148:149], off
	v_lshl_add_u64 v[148:149], s[40:41], 0, v[140:141]
	s_add_i32 m0, s34, 0xe000
	s_nop 0
	global_load_lds_dwordx4 v[148:149], off
	s_waitcnt lgkmcnt(8)
	s_barrier
	s_setprio 1
	s_waitcnt lgkmcnt(7)
	v_mfma_f32_16x16x32_bf16 v[126:129], v[154:157], v[170:173], v[126:129]
	v_mfma_f32_16x16x32_bf16 v[122:125], v[162:165], v[170:173], v[122:125]
	s_waitcnt lgkmcnt(6)
	v_mfma_f32_16x16x32_bf16 v[114:117], v[154:157], v[178:181], v[114:117]
	v_mfma_f32_16x16x32_bf16 v[106:109], v[162:165], v[178:181], v[106:109]
	s_waitcnt lgkmcnt(5)
	v_mfma_f32_16x16x32_bf16 v[98:101], v[154:157], v[186:189], v[98:101]
	v_mfma_f32_16x16x32_bf16 v[90:93], v[162:165], v[186:189], v[90:93]
	s_waitcnt lgkmcnt(4)
	v_mfma_f32_16x16x32_bf16 v[82:85], v[154:157], v[194:197], v[82:85]
	v_mfma_f32_16x16x32_bf16 v[74:77], v[162:165], v[194:197], v[74:77]
	s_waitcnt lgkmcnt(3)
	v_mfma_f32_16x16x32_bf16 v[126:129], v[158:161], v[174:177], v[126:129]
	v_mfma_f32_16x16x32_bf16 v[122:125], v[166:169], v[174:177], v[122:125]
	s_waitcnt lgkmcnt(2)
	v_mfma_f32_16x16x32_bf16 v[114:117], v[158:161], v[182:185], v[114:117]
	v_mfma_f32_16x16x32_bf16 v[106:109], v[166:169], v[182:185], v[106:109]
	s_waitcnt lgkmcnt(1)
	v_mfma_f32_16x16x32_bf16 v[98:101], v[158:161], v[190:193], v[98:101]
	v_mfma_f32_16x16x32_bf16 v[90:93], v[166:169], v[190:193], v[90:93]
	s_waitcnt lgkmcnt(0)
	v_mfma_f32_16x16x32_bf16 v[82:85], v[158:161], v[198:201], v[82:85]
	v_mfma_f32_16x16x32_bf16 v[74:77], v[166:169], v[198:201], v[74:77]
	s_setprio 0
	s_barrier
	s_add_i32 s71, s51, s33
	v_lshl_add_u64 v[148:149], s[42:43], 0, v[132:133]
	s_mov_b32 m0, s71
	ds_read_b128 v[202:205], v153
	ds_read_b128 v[210:213], v153 offset:2048
	ds_read_b128 v[206:209], v153 offset:1024
	ds_read_b128 v[214:217], v153 offset:3072
	global_load_lds_dwordx4 v[148:149], off
	v_lshl_add_u64 v[218:219], s[42:43], 0, v[136:137]
	s_add_i32 m0, s71, 0x2000
	s_nop 0
	global_load_lds_dwordx4 v[218:219], off
	s_barrier
	s_setprio 1
	s_waitcnt lgkmcnt(2)
	v_mfma_f32_16x16x32_bf16 v[118:121], v[202:205], v[170:173], v[118:121]
	v_mfma_f32_16x16x32_bf16 v[110:113], v[210:213], v[170:173], v[110:113]
	v_mfma_f32_16x16x32_bf16 v[102:105], v[202:205], v[178:181], v[102:105]
	v_mfma_f32_16x16x32_bf16 v[94:97], v[210:213], v[178:181], v[94:97]
	v_mfma_f32_16x16x32_bf16 v[86:89], v[202:205], v[186:189], v[86:89]
	v_mfma_f32_16x16x32_bf16 v[78:81], v[210:213], v[186:189], v[78:81]
	v_mfma_f32_16x16x32_bf16 v[70:73], v[202:205], v[194:197], v[70:73]
	v_mfma_f32_16x16x32_bf16 v[66:69], v[210:213], v[194:197], v[66:69]
	s_waitcnt lgkmcnt(0)
	v_mfma_f32_16x16x32_bf16 v[118:121], v[206:209], v[174:177], v[118:121]
	v_mfma_f32_16x16x32_bf16 v[110:113], v[214:217], v[174:177], v[110:113]
	v_mfma_f32_16x16x32_bf16 v[102:105], v[206:209], v[182:185], v[102:105]
	v_mfma_f32_16x16x32_bf16 v[94:97], v[214:217], v[182:185], v[94:97]
	v_mfma_f32_16x16x32_bf16 v[86:89], v[206:209], v[190:193], v[86:89]
	v_mfma_f32_16x16x32_bf16 v[78:81], v[214:217], v[190:193], v[78:81]
	v_mfma_f32_16x16x32_bf16 v[70:73], v[206:209], v[198:201], v[70:73]
	v_mfma_f32_16x16x32_bf16 v[66:69], v[214:217], v[198:201], v[66:69]
	s_setprio 0
	s_mov_b32 m0, s34
	v_lshl_add_u64 v[220:221], s[44:45], 0, v[130:131]
	s_barrier
	ds_read_b128 v[170:173], v152 offset:16384
	ds_read_b128 v[178:181], v152 offset:18432
	ds_read_b128 v[186:189], v152 offset:20480
	ds_read_b128 v[194:197], v152 offset:22528
	ds_read_b128 v[174:177], v152 offset:17408
	ds_read_b128 v[182:185], v152 offset:19456
	ds_read_b128 v[190:193], v152 offset:21504
	ds_read_b128 v[198:201], v152 offset:23552
	global_load_lds_dwordx4 v[220:221], off
	v_lshl_add_u64 v[222:223], s[44:45], 0, v[134:135]
	s_mov_b32 m0, s35
	s_nop 0
	global_load_lds_dwordx4 v[222:223], off
	s_barrier
	s_setprio 1
	s_waitcnt lgkmcnt(7)
	v_mfma_f32_16x16x32_bf16 v[62:65], v[154:157], v[170:173], v[62:65]
	v_mfma_f32_16x16x32_bf16 v[58:61], v[162:165], v[170:173], v[58:61]
	s_waitcnt lgkmcnt(6)
	v_mfma_f32_16x16x32_bf16 v[54:57], v[154:157], v[178:181], v[54:57]
	v_mfma_f32_16x16x32_bf16 v[46:49], v[162:165], v[178:181], v[46:49]
	s_waitcnt lgkmcnt(5)
	v_mfma_f32_16x16x32_bf16 v[38:41], v[154:157], v[186:189], v[38:41]
	v_mfma_f32_16x16x32_bf16 v[30:33], v[162:165], v[186:189], v[30:33]
	s_waitcnt lgkmcnt(4)
	v_mfma_f32_16x16x32_bf16 v[22:25], v[154:157], v[194:197], v[22:25]
	v_mfma_f32_16x16x32_bf16 v[14:17], v[162:165], v[194:197], v[14:17]
	s_waitcnt lgkmcnt(3)
	v_mfma_f32_16x16x32_bf16 v[62:65], v[158:161], v[174:177], v[62:65]
	v_mfma_f32_16x16x32_bf16 v[58:61], v[166:169], v[174:177], v[58:61]
	s_waitcnt lgkmcnt(2)
	v_mfma_f32_16x16x32_bf16 v[54:57], v[158:161], v[182:185], v[54:57]
	v_mfma_f32_16x16x32_bf16 v[46:49], v[166:169], v[182:185], v[46:49]
	s_waitcnt lgkmcnt(1)
	v_mfma_f32_16x16x32_bf16 v[38:41], v[158:161], v[190:193], v[38:41]
	v_mfma_f32_16x16x32_bf16 v[30:33], v[166:169], v[190:193], v[30:33]
	s_waitcnt lgkmcnt(0)
	v_mfma_f32_16x16x32_bf16 v[22:25], v[158:161], v[198:201], v[22:25]
	v_mfma_f32_16x16x32_bf16 v[14:17], v[166:169], v[198:201], v[14:17]
	s_setprio 0
	s_barrier
	s_add_u32 s72, s42, 0x80000
	s_addc_u32 s73, s43, 0
	s_add_i32 s71, s60, s33
	v_lshl_add_u64 v[154:155], s[72:73], 0, v[132:133]
	s_mov_b32 m0, s71
	s_nop 0
	global_load_lds_dwordx4 v[154:155], off
	v_lshl_add_u64 v[154:155], s[72:73], 0, v[136:137]
	s_add_i32 m0, s71, 0x2000
	s_nop 0
	global_load_lds_dwordx4 v[154:155], off
	s_waitcnt vmcnt(6)
	s_barrier
	s_setprio 1
	v_mfma_f32_16x16x32_bf16 v[50:53], v[202:205], v[170:173], v[50:53]
	v_mfma_f32_16x16x32_bf16 v[42:45], v[210:213], v[170:173], v[42:45]
	v_mfma_f32_16x16x32_bf16 v[34:37], v[202:205], v[178:181], v[34:37]
	v_mfma_f32_16x16x32_bf16 v[26:29], v[210:213], v[178:181], v[26:29]
	v_mfma_f32_16x16x32_bf16 v[18:21], v[202:205], v[186:189], v[18:21]
	v_mfma_f32_16x16x32_bf16 v[10:13], v[210:213], v[186:189], v[10:13]
	v_mfma_f32_16x16x32_bf16 v[6:9], v[202:205], v[194:197], v[6:9]
	v_mfma_f32_16x16x32_bf16 v[2:5], v[210:213], v[194:197], v[2:5]
	v_mfma_f32_16x16x32_bf16 v[50:53], v[206:209], v[174:177], v[50:53]
	v_mfma_f32_16x16x32_bf16 v[42:45], v[214:217], v[174:177], v[42:45]
	v_mfma_f32_16x16x32_bf16 v[34:37], v[206:209], v[182:185], v[34:37]
	v_mfma_f32_16x16x32_bf16 v[26:29], v[214:217], v[182:185], v[26:29]
	v_mfma_f32_16x16x32_bf16 v[18:21], v[206:209], v[190:193], v[18:21]
	v_mfma_f32_16x16x32_bf16 v[10:13], v[214:217], v[190:193], v[10:13]
	v_mfma_f32_16x16x32_bf16 v[6:9], v[206:209], v[198:201], v[6:9]
	v_mfma_f32_16x16x32_bf16 v[2:5], v[214:217], v[198:201], v[2:5]
	s_setprio 0
	s_add_i32 s71, 0, 0x18000
	v_add_u32_e32 v166, s71, v147
	s_barrier
	ds_read_b128 v[154:157], v166
	ds_read_b128 v[158:161], v166 offset:1024
	ds_read_b128 v[162:165], v166 offset:2048
	ds_read_b128 v[166:169], v166 offset:3072
	s_add_u32 s44, s44, 0x80000
	s_addc_u32 s45, s45, 0
	s_mov_b32 m0, s39
	v_lshl_add_u64 v[202:203], s[44:45], 0, v[130:131]
	ds_read_b128 v[170:173], v152 offset:32768
	ds_read_b128 v[178:181], v152 offset:34816
	ds_read_b128 v[186:189], v152 offset:36864
	ds_read_b128 v[194:197], v152 offset:38912
	ds_read_b128 v[174:177], v152 offset:33792
	ds_read_b128 v[182:185], v152 offset:35840
	ds_read_b128 v[190:193], v152 offset:37888
	ds_read_b128 v[198:201], v152 offset:39936
	global_load_lds_dwordx4 v[202:203], off
	v_lshl_add_u64 v[202:203], s[44:45], 0, v[134:135]
	s_mov_b32 m0, s46
	s_nop 0
	global_load_lds_dwordx4 v[202:203], off
	s_waitcnt lgkmcnt(8)
	s_barrier
	s_setprio 1
	s_waitcnt lgkmcnt(7)
	v_mfma_f32_16x16x32_bf16 v[126:129], v[154:157], v[170:173], v[126:129]
	v_mfma_f32_16x16x32_bf16 v[122:125], v[162:165], v[170:173], v[122:125]
	s_waitcnt lgkmcnt(6)
	v_mfma_f32_16x16x32_bf16 v[114:117], v[154:157], v[178:181], v[114:117]
	v_mfma_f32_16x16x32_bf16 v[106:109], v[162:165], v[178:181], v[106:109]
	s_waitcnt lgkmcnt(5)
	v_mfma_f32_16x16x32_bf16 v[98:101], v[154:157], v[186:189], v[98:101]
	v_mfma_f32_16x16x32_bf16 v[90:93], v[162:165], v[186:189], v[90:93]
	s_waitcnt lgkmcnt(4)
	v_mfma_f32_16x16x32_bf16 v[82:85], v[154:157], v[194:197], v[82:85]
	v_mfma_f32_16x16x32_bf16 v[74:77], v[162:165], v[194:197], v[74:77]
	s_waitcnt lgkmcnt(3)
	v_mfma_f32_16x16x32_bf16 v[126:129], v[158:161], v[174:177], v[126:129]
	v_mfma_f32_16x16x32_bf16 v[122:125], v[166:169], v[174:177], v[122:125]
	s_waitcnt lgkmcnt(2)
	v_mfma_f32_16x16x32_bf16 v[114:117], v[158:161], v[182:185], v[114:117]
	v_mfma_f32_16x16x32_bf16 v[106:109], v[166:169], v[182:185], v[106:109]
	s_waitcnt lgkmcnt(1)
	v_mfma_f32_16x16x32_bf16 v[98:101], v[158:161], v[190:193], v[98:101]
	v_mfma_f32_16x16x32_bf16 v[90:93], v[166:169], v[190:193], v[90:93]
	s_waitcnt lgkmcnt(0)
	v_mfma_f32_16x16x32_bf16 v[82:85], v[158:161], v[198:201], v[82:85]
	v_mfma_f32_16x16x32_bf16 v[74:77], v[166:169], v[198:201], v[74:77]
	s_setprio 0
	s_barrier
	s_add_i32 s44, 0, 0x1c000
	s_add_i32 s45, s71, s33
	v_add_u32_e32 v214, s44, v147
	v_lshl_add_u64 v[148:149], v[148:149], 0, s[10:11]
	s_mov_b32 m0, s45
	ds_read_b128 v[202:205], v214
	ds_read_b128 v[210:213], v214 offset:2048
	ds_read_b128 v[206:209], v214 offset:1024
	ds_read_b128 v[214:217], v214 offset:3072
	global_load_lds_dwordx4 v[148:149], off
	v_lshl_add_u64 v[148:149], v[218:219], 0, s[10:11]
	s_add_i32 m0, s45, 0x2000
	s_nop 0
	global_load_lds_dwordx4 v[148:149], off
	s_barrier
	s_setprio 1
	s_waitcnt lgkmcnt(2)
	v_mfma_f32_16x16x32_bf16 v[118:121], v[202:205], v[170:173], v[118:121]
	v_mfma_f32_16x16x32_bf16 v[110:113], v[210:213], v[170:173], v[110:113]
	v_mfma_f32_16x16x32_bf16 v[102:105], v[202:205], v[178:181], v[102:105]
	v_mfma_f32_16x16x32_bf16 v[94:97], v[210:213], v[178:181], v[94:97]
	v_mfma_f32_16x16x32_bf16 v[86:89], v[202:205], v[186:189], v[86:89]
	v_mfma_f32_16x16x32_bf16 v[78:81], v[210:213], v[186:189], v[78:81]
	v_mfma_f32_16x16x32_bf16 v[70:73], v[202:205], v[194:197], v[70:73]
	v_mfma_f32_16x16x32_bf16 v[66:69], v[210:213], v[194:197], v[66:69]
	s_waitcnt lgkmcnt(0)
	v_mfma_f32_16x16x32_bf16 v[118:121], v[206:209], v[174:177], v[118:121]
	v_mfma_f32_16x16x32_bf16 v[110:113], v[214:217], v[174:177], v[110:113]
	v_mfma_f32_16x16x32_bf16 v[102:105], v[206:209], v[182:185], v[102:105]
	v_mfma_f32_16x16x32_bf16 v[94:97], v[214:217], v[182:185], v[94:97]
	v_mfma_f32_16x16x32_bf16 v[86:89], v[206:209], v[190:193], v[86:89]
	v_mfma_f32_16x16x32_bf16 v[78:81], v[214:217], v[190:193], v[78:81]
	v_mfma_f32_16x16x32_bf16 v[70:73], v[206:209], v[198:201], v[70:73]
	v_mfma_f32_16x16x32_bf16 v[66:69], v[214:217], v[198:201], v[66:69]
	s_setprio 0
	s_mov_b32 m0, s48
	v_lshl_add_u64 v[148:149], v[220:221], 0, s[10:11]
	s_barrier
	ds_read_b128 v[170:173], v152 offset:49152
	ds_read_b128 v[178:181], v152 offset:51200
	ds_read_b128 v[186:189], v152 offset:53248
	ds_read_b128 v[194:197], v152 offset:55296
	ds_read_b128 v[174:177], v152 offset:50176
	ds_read_b128 v[182:185], v152 offset:52224
	ds_read_b128 v[190:193], v152 offset:54272
	ds_read_b128 v[198:201], v152 offset:56320
	global_load_lds_dwordx4 v[148:149], off
	v_lshl_add_u64 v[148:149], v[222:223], 0, s[10:11]
	s_mov_b32 m0, s49
	s_nop 0
	global_load_lds_dwordx4 v[148:149], off
	s_barrier
	s_setprio 1
	s_waitcnt lgkmcnt(7)
	v_mfma_f32_16x16x32_bf16 v[62:65], v[154:157], v[170:173], v[62:65]
	v_mfma_f32_16x16x32_bf16 v[58:61], v[162:165], v[170:173], v[58:61]
	s_waitcnt lgkmcnt(6)
	v_mfma_f32_16x16x32_bf16 v[54:57], v[154:157], v[178:181], v[54:57]
	v_mfma_f32_16x16x32_bf16 v[46:49], v[162:165], v[178:181], v[46:49]
	s_waitcnt lgkmcnt(5)
	v_mfma_f32_16x16x32_bf16 v[38:41], v[154:157], v[186:189], v[38:41]
	v_mfma_f32_16x16x32_bf16 v[30:33], v[162:165], v[186:189], v[30:33]
	s_waitcnt lgkmcnt(4)
	v_mfma_f32_16x16x32_bf16 v[22:25], v[154:157], v[194:197], v[22:25]
	v_mfma_f32_16x16x32_bf16 v[14:17], v[162:165], v[194:197], v[14:17]
	s_waitcnt lgkmcnt(3)
	v_mfma_f32_16x16x32_bf16 v[62:65], v[158:161], v[174:177], v[62:65]
	v_mfma_f32_16x16x32_bf16 v[58:61], v[166:169], v[174:177], v[58:61]
	s_waitcnt lgkmcnt(2)
	v_mfma_f32_16x16x32_bf16 v[54:57], v[158:161], v[182:185], v[54:57]
	v_mfma_f32_16x16x32_bf16 v[46:49], v[166:169], v[182:185], v[46:49]
	s_waitcnt lgkmcnt(1)
	v_mfma_f32_16x16x32_bf16 v[38:41], v[158:161], v[190:193], v[38:41]
	v_mfma_f32_16x16x32_bf16 v[30:33], v[166:169], v[190:193], v[30:33]
	s_waitcnt lgkmcnt(0)
	v_mfma_f32_16x16x32_bf16 v[22:25], v[158:161], v[198:201], v[22:25]
	v_mfma_f32_16x16x32_bf16 v[14:17], v[166:169], v[198:201], v[14:17]
	s_setprio 0
	s_barrier
	s_add_u32 s42, s42, 0x80080
	s_addc_u32 s43, s43, 0
	s_add_i32 s44, s44, s33
	v_lshl_add_u64 v[148:149], s[42:43], 0, v[132:133]
	s_mov_b32 m0, s44
	s_nop 0
	global_load_lds_dwordx4 v[148:149], off
	v_lshl_add_u64 v[148:149], s[42:43], 0, v[136:137]
	s_add_i32 m0, s44, 0x2000
	s_nop 0
	global_load_lds_dwordx4 v[148:149], off
	s_waitcnt vmcnt(6)
	s_barrier
	s_setprio 1
	v_mfma_f32_16x16x32_bf16 v[50:53], v[202:205], v[170:173], v[50:53]
	v_mfma_f32_16x16x32_bf16 v[42:45], v[210:213], v[170:173], v[42:45]
	v_mfma_f32_16x16x32_bf16 v[34:37], v[202:205], v[178:181], v[34:37]
	v_mfma_f32_16x16x32_bf16 v[26:29], v[210:213], v[178:181], v[26:29]
	v_mfma_f32_16x16x32_bf16 v[18:21], v[202:205], v[186:189], v[18:21]
	v_mfma_f32_16x16x32_bf16 v[10:13], v[210:213], v[186:189], v[10:13]
	v_mfma_f32_16x16x32_bf16 v[6:9], v[202:205], v[194:197], v[6:9]
	v_mfma_f32_16x16x32_bf16 v[2:5], v[210:213], v[194:197], v[2:5]
	v_mfma_f32_16x16x32_bf16 v[50:53], v[206:209], v[174:177], v[50:53]
	v_mfma_f32_16x16x32_bf16 v[42:45], v[214:217], v[174:177], v[42:45]
	v_mfma_f32_16x16x32_bf16 v[34:37], v[206:209], v[182:185], v[34:37]
	v_mfma_f32_16x16x32_bf16 v[26:29], v[214:217], v[182:185], v[26:29]
	v_mfma_f32_16x16x32_bf16 v[18:21], v[206:209], v[190:193], v[18:21]
	v_mfma_f32_16x16x32_bf16 v[10:13], v[214:217], v[190:193], v[10:13]
	v_mfma_f32_16x16x32_bf16 v[6:9], v[206:209], v[198:201], v[6:9]
	v_mfma_f32_16x16x32_bf16 v[2:5], v[214:217], v[198:201], v[2:5]
	s_setprio 0
	s_add_i32 s70, s70, 2
	s_add_u32 s40, s40, 0x100
	s_addc_u32 s41, s41, 0
	s_add_u32 s68, s68, 0x100
	s_addc_u32 s69, s69, 0
	s_cmp_gt_u32 s70, 29
	s_barrier
	s_cbranch_scc0 .LBB0_909
	v_lshl_add_u32 v154, s38, 8, v1
	v_lshl_or_b32 v148, s65, 8, v150
	v_ashrrev_i32_e32 v155, 31, v154
	v_ashrrev_i32_e32 v149, 31, v148
	v_lshlrev_b64 v[156:157], 12, v[154:155]
	v_lshl_add_u64 v[156:157], s[8:9], 0, v[156:157]
	v_lshlrev_b64 v[158:159], 1, v[148:149]
	v_lshl_add_u64 v[148:149], v[156:157], 0, v[158:159]
	v_cvt_pk_bf16_f32 v126, v126, v127
	v_cvt_pk_bf16_f32 v127, v128, v129
	v_cvt_pk_bf16_f32 v128, v122, v123
	v_cvt_pk_bf16_f32 v129, v124, v125
	global_store_dwordx4 v[148:149], v[126:129], off
	v_cvt_pk_bf16_f32 v118, v118, v119
	v_cvt_pk_bf16_f32 v119, v120, v121
	v_cvt_pk_bf16_f32 v120, v110, v111
	v_or_b32_e32 v110, 16, v154
	v_ashrrev_i32_e32 v111, 31, v110
	v_lshlrev_b64 v[110:111], 12, v[110:111]
	v_lshl_add_u64 v[110:111], s[8:9], 0, v[110:111]
	v_cvt_pk_bf16_f32 v121, v112, v113
	global_store_dwordx4 v[148:149], v[118:121], off offset:256
	s_mov_b32 s65, s22
	s_mov_b32 s38, s24
	v_lshl_add_u64 v[118:119], v[110:111], 0, v[158:159]
	v_cvt_pk_bf16_f32 v110, v114, v115
	v_cvt_pk_bf16_f32 v111, v116, v117
	v_cvt_pk_bf16_f32 v112, v106, v107
	v_cvt_pk_bf16_f32 v113, v108, v109
	global_store_dwordx4 v[118:119], v[110:113], off
	v_cvt_pk_bf16_f32 v102, v102, v103
	v_cvt_pk_bf16_f32 v103, v104, v105
	v_cvt_pk_bf16_f32 v104, v94, v95
	v_or_b32_e32 v94, 32, v154
	v_ashrrev_i32_e32 v95, 31, v94
	v_lshlrev_b64 v[94:95], 12, v[94:95]
	v_lshl_add_u64 v[94:95], s[8:9], 0, v[94:95]
	v_cvt_pk_bf16_f32 v105, v96, v97
	global_store_dwordx4 v[118:119], v[102:105], off offset:256
	s_mov_b64 s[42:43], s[36:37]
	s_mov_b64 s[40:41], s[26:27]
	v_lshl_add_u64 v[102:103], v[94:95], 0, v[158:159]
	v_cvt_pk_bf16_f32 v94, v98, v99
	v_cvt_pk_bf16_f32 v95, v100, v101
	v_cvt_pk_bf16_f32 v96, v90, v91
	v_cvt_pk_bf16_f32 v97, v92, v93
	global_store_dwordx4 v[102:103], v[94:97], off
	v_cvt_pk_bf16_f32 v86, v86, v87
	v_cvt_pk_bf16_f32 v87, v88, v89
	v_cvt_pk_bf16_f32 v88, v78, v79
	v_or_b32_e32 v78, 48, v154
	v_ashrrev_i32_e32 v79, 31, v78
	v_lshlrev_b64 v[78:79], 12, v[78:79]
	v_lshl_add_u64 v[78:79], s[8:9], 0, v[78:79]
	v_cvt_pk_bf16_f32 v89, v80, v81
	global_store_dwordx4 v[102:103], v[86:89], off offset:256
	s_nop 1
	v_lshl_add_u64 v[86:87], v[78:79], 0, v[158:159]
	v_cvt_pk_bf16_f32 v78, v82, v83
	v_cvt_pk_bf16_f32 v79, v84, v85
	v_cvt_pk_bf16_f32 v80, v74, v75
	v_cvt_pk_bf16_f32 v81, v76, v77
	global_store_dwordx4 v[86:87], v[78:81], off
	v_cvt_pk_bf16_f32 v70, v70, v71
	v_cvt_pk_bf16_f32 v71, v72, v73
	v_cvt_pk_bf16_f32 v72, v66, v67
	v_cvt_pk_bf16_f32 v73, v68, v69
	global_store_dwordx4 v[86:87], v[70:73], off offset:256
	v_cvt_pk_bf16_f32 v62, v62, v63
	v_cvt_pk_bf16_f32 v63, v64, v65
	v_cvt_pk_bf16_f32 v64, v58, v59
	v_add_co_u32_e32 v58, vcc, s61, v148
	v_lshl_add_u64 v[66:67], v[148:149], 0, s[6:7]
	s_nop 0
	v_addc_co_u32_e32 v59, vcc, 0, v149, vcc
	v_cvt_pk_bf16_f32 v65, v60, v61
	global_store_dwordx4 v[58:59], v[62:65], off
	v_cvt_pk_bf16_f32 v50, v50, v51
	v_cvt_pk_bf16_f32 v51, v52, v53
	v_cvt_pk_bf16_f32 v52, v42, v43
	v_cvt_pk_bf16_f32 v53, v44, v45
	global_store_dwordx4 v[66:67], v[50:53], off offset:256
	v_cvt_pk_bf16_f32 v42, v54, v55
	v_cvt_pk_bf16_f32 v43, v56, v57
	v_cvt_pk_bf16_f32 v44, v46, v47
	v_add_co_u32_e32 v46, vcc, s62, v148
	s_nop 0
	v_lshl_add_u64 v[50:51], v[148:149], 0, s[16:17]
	v_addc_co_u32_e32 v47, vcc, 0, v149, vcc
	v_cvt_pk_bf16_f32 v45, v48, v49
	global_store_dwordx4 v[46:47], v[42:45], off
	v_cvt_pk_bf16_f32 v34, v34, v35
	v_cvt_pk_bf16_f32 v35, v36, v37
	v_cvt_pk_bf16_f32 v36, v26, v27
	v_cvt_pk_bf16_f32 v37, v28, v29
	global_store_dwordx4 v[50:51], v[34:37], off offset:256
	v_cvt_pk_bf16_f32 v26, v38, v39
	v_cvt_pk_bf16_f32 v27, v40, v41
	v_cvt_pk_bf16_f32 v28, v30, v31
	v_add_co_u32_e32 v30, vcc, s63, v148
	s_nop 0
	v_lshl_add_u64 v[34:35], v[148:149], 0, s[18:19]
	v_addc_co_u32_e32 v31, vcc, 0, v149, vcc
	v_cvt_pk_bf16_f32 v29, v32, v33
	global_store_dwordx4 v[30:31], v[26:29], off
	v_cvt_pk_bf16_f32 v18, v18, v19
	v_cvt_pk_bf16_f32 v19, v20, v21
	v_cvt_pk_bf16_f32 v20, v10, v11
	v_cvt_pk_bf16_f32 v21, v12, v13
	global_store_dwordx4 v[34:35], v[18:21], off offset:256
	v_cvt_pk_bf16_f32 v10, v22, v23
	v_cvt_pk_bf16_f32 v11, v24, v25
	v_cvt_pk_bf16_f32 v12, v14, v15
	v_add_co_u32_e32 v14, vcc, s64, v148
	s_nop 0
	v_lshl_add_u64 v[18:19], v[148:149], 0, s[20:21]
	v_addc_co_u32_e32 v15, vcc, 0, v149, vcc
	s_and_b64 vcc, exec, s[0:1]
	v_cvt_pk_bf16_f32 v13, v16, v17
	global_store_dwordx4 v[14:15], v[10:13], off
	v_cvt_pk_bf16_f32 v6, v6, v7
	v_cvt_pk_bf16_f32 v7, v8, v9
	v_cvt_pk_bf16_f32 v8, v2, v3
	v_cvt_pk_bf16_f32 v9, v4, v5
	global_store_dwordx4 v[18:19], v[6:9], off offset:256
	s_cbranch_vccz .LBB0_902
	s_waitcnt vmcnt(0)
	s_cmpk_gt_u32 s3, 0xff
	s_cbranch_scc1 .LBB0_913
	s_barrier
